# speedup vs baseline: 1.0253x; 1.0008x over previous
; __device__ __forceinline__ unsigned pack2(float a, float b) { return (unsigned)f2bf(a) | ((unsigned)f2bf(b) << 16); }
; __device__ __forceinline__ float lo16(unsigned v) { return __uint_as_float(v << 16); }
; __device__ __forceinline__ float hi16(unsigned v) { return __uint_as_float(v & 0xffff0000u); }
; __device__ __forceinline__ void phase_scan(const Params& p, unsigned* st, int npairs, int pairs_per_head_shift, int mode) {
;     ...
;   for (int e = blockIdx.x * 256 + tid; e < npairs; e += gridDim.x * 256) {
;     int h = e >> pairs_per_head_shift;
;     float r0 = 0.f, r1 = 0.f;
;     float rdec = 1.f;
;     if (mode == 1) rdec = expf(128.f * logf(1.f - exp2f(-5.f - (float)h)));
;     for (int c0 = 0; c0 < NCH; c0 += 8) {
;       unsigned v[8];
;       float dc[8];
; #pragma unroll
;       for (int i = 0; i < 8; i++) {
;         int c = c0 + i;
;         if (c < NCH) {
;           v[i] = st[(size_t)c * npairs + e];
;           dc[i] = (mode == 0) ? expf(acs[((size_t)c * 16 + h) * 128 + 127]) : rdec;
;         } else { v[i] = 0; dc[i] = 0.f; }
;       }
; #pragma unroll
;       for (int i = 0; i < 8; i++) {
;         int c = c0 + i;
;         if (c < NCH) {
;           *(st + (size_t)c * npairs + e) = pack2(r0, r1);
;           r0 = r0 * dc[i] + lo16(v[i]);
;           r1 = r1 * dc[i] + hi16(v[i]);
;         }
;       }
;     }
;   }
.LBB0_1190:
	v_mov_b32_e32 v17, 0x7fff
	v_mov_b32_e32 v18, 0xffff0000
	v_mov_b32_e32 v19, 0x3fb8aa3b
	v_mov_b32_e32 v16, 0x7f800000
	v_lshlrev_b32_e32 v26, 2, v0
	v_mov_b32_e32 v20, 0
	v_mov_b32_e32 v21, 0
	v_mov_b32_e32 v27, v26
	v_add_u32_e32 v28, 0x2000000, v26
	v_ashrrev_i32_e32 v30, 12, v0
	v_lshlrev_b32_e32 v30, 9, v30
	v_add_u32_e32 v31, 0x100000, v30
	global_load_dword v40, v26, s[6:7]
	v_add_u32_e32 v26, 0x40000, v26
	global_load_dword v60, v30, s[8:9]
	v_add_u32_e32 v30, 0x2000, v30
	global_load_dword v41, v26, s[6:7]
	v_add_u32_e32 v26, 0x40000, v26
	global_load_dword v61, v30, s[8:9]
	v_add_u32_e32 v30, 0x2000, v30
	global_load_dword v42, v26, s[6:7]
	v_add_u32_e32 v26, 0x40000, v26
	global_load_dword v62, v30, s[8:9]
	v_add_u32_e32 v30, 0x2000, v30
	global_load_dword v43, v26, s[6:7]
	v_add_u32_e32 v26, 0x40000, v26
	global_load_dword v63, v30, s[8:9]
	v_add_u32_e32 v30, 0x2000, v30
	global_load_dword v44, v26, s[6:7]
	v_add_u32_e32 v26, 0x40000, v26
	global_load_dword v64, v30, s[8:9]
	v_add_u32_e32 v30, 0x2000, v30
	global_load_dword v45, v26, s[6:7]
	v_add_u32_e32 v26, 0x40000, v26
	global_load_dword v65, v30, s[8:9]
	v_add_u32_e32 v30, 0x2000, v30
	global_load_dword v46, v26, s[6:7]
	v_add_u32_e32 v26, 0x40000, v26
	global_load_dword v66, v30, s[8:9]
	v_add_u32_e32 v30, 0x2000, v30
	global_load_dword v47, v26, s[6:7]
	v_add_u32_e32 v26, 0x40000, v26
	global_load_dword v67, v30, s[8:9]
	v_add_u32_e32 v30, 0x2000, v30
	global_load_dword v48, v26, s[6:7]
	v_add_u32_e32 v26, 0x40000, v26
	global_load_dword v68, v30, s[8:9]
	v_add_u32_e32 v30, 0x2000, v30
	global_load_dword v49, v26, s[6:7]
	v_add_u32_e32 v26, 0x40000, v26
	global_load_dword v69, v30, s[8:9]
	v_add_u32_e32 v30, 0x2000, v30
	global_load_dword v50, v26, s[6:7]
	v_add_u32_e32 v26, 0x40000, v26
	global_load_dword v70, v30, s[8:9]
	v_add_u32_e32 v30, 0x2000, v30
	global_load_dword v51, v26, s[6:7]
	v_add_u32_e32 v26, 0x40000, v26
	global_load_dword v71, v30, s[8:9]
	v_add_u32_e32 v30, 0x2000, v30
	global_load_dword v52, v26, s[6:7]
	v_add_u32_e32 v26, 0x40000, v26
	global_load_dword v72, v30, s[8:9]
	v_add_u32_e32 v30, 0x2000, v30
	global_load_dword v53, v26, s[6:7]
	v_add_u32_e32 v26, 0x40000, v26
	global_load_dword v73, v30, s[8:9]
	v_add_u32_e32 v30, 0x2000, v30
	global_load_dword v54, v26, s[6:7]
	v_add_u32_e32 v26, 0x40000, v26
	global_load_dword v74, v30, s[8:9]
	v_add_u32_e32 v30, 0x2000, v30
	global_load_dword v55, v26, s[6:7]
	v_add_u32_e32 v26, 0x40000, v26
	global_load_dword v75, v30, s[8:9]
	v_add_u32_e32 v30, 0x2000, v30
	s_waitcnt vmcnt(30)
	v_mul_f32_e32 v13, 0x3fb8aa3b, v60
	v_fma_f32 v14, v60, v19, -v13
	v_rndne_f32_e32 v15, v13
	v_fmac_f32_e32 v14, 0x32a5705f, v60
	v_sub_f32_e32 v13, v13, v15
	v_add_f32_e32 v13, v13, v14
	v_exp_f32_e32 v13, v13
	v_cvt_i32_f32_e32 v14, v15
	v_cmp_ngt_f32_e32 vcc, 0xc2ce8ed0, v60
	v_ldexp_f32 v13, v13, v14
	s_nop 0
	v_cndmask_b32_e32 v13, 0, v13, vcc
	v_cmp_nlt_f32_e32 vcc, 0x42b17218, v60
	s_nop 1
	v_cndmask_b32_e32 v12, v16, v13, vcc
	v_bfe_u32 v24, v20, 16, 1
	v_add3_u32 v24, v20, v24, v17
	v_bfe_u32 v25, v21, 16, 1
	v_lshrrev_b32_e32 v24, 16, v24
	v_add3_u32 v25, v21, v25, v17
	v_and_or_b32 v24, v25, v18, v24
	global_store_dword v27, v24, s[6:7]
	v_add_u32_e32 v27, 0x40000, v27
	v_lshlrev_b32_e32 v22, 16, v40
	v_and_b32_e32 v23, 0xffff0000, v40
	v_fmac_f32_e32 v22, v12, v20
	v_fmac_f32_e32 v23, v12, v21
	v_min_u32_e32 v26, v26, v28
	global_load_dword v40, v26, s[6:7]
	v_add_u32_e32 v26, 0x40000, v26
	v_min_u32_e32 v30, v30, v31
	global_load_dword v60, v30, s[8:9]
	v_add_u32_e32 v30, 0x2000, v30
	s_waitcnt vmcnt(31)
	v_mul_f32_e32 v13, 0x3fb8aa3b, v61
	v_fma_f32 v14, v61, v19, -v13
	v_rndne_f32_e32 v15, v13
	v_fmac_f32_e32 v14, 0x32a5705f, v61
	v_sub_f32_e32 v13, v13, v15
	v_add_f32_e32 v13, v13, v14
	v_exp_f32_e32 v13, v13
	v_cvt_i32_f32_e32 v14, v15
	v_cmp_ngt_f32_e32 vcc, 0xc2ce8ed0, v61
	v_ldexp_f32 v13, v13, v14
	s_nop 0
	v_cndmask_b32_e32 v13, 0, v13, vcc
	v_cmp_nlt_f32_e32 vcc, 0x42b17218, v61
	s_nop 1
	v_cndmask_b32_e32 v12, v16, v13, vcc
	v_bfe_u32 v24, v22, 16, 1
	v_add3_u32 v24, v22, v24, v17
	v_bfe_u32 v25, v23, 16, 1
	v_lshrrev_b32_e32 v24, 16, v24
	v_add3_u32 v25, v23, v25, v17
	v_and_or_b32 v24, v25, v18, v24
	global_store_dword v27, v24, s[6:7]
	v_add_u32_e32 v27, 0x40000, v27
	v_lshlrev_b32_e32 v20, 16, v41
	v_and_b32_e32 v21, 0xffff0000, v41
	v_fmac_f32_e32 v20, v12, v22
	v_fmac_f32_e32 v21, v12, v23
	v_min_u32_e32 v26, v26, v28
	global_load_dword v41, v26, s[6:7]
	v_add_u32_e32 v26, 0x40000, v26
	v_min_u32_e32 v30, v30, v31
	global_load_dword v61, v30, s[8:9]
	v_add_u32_e32 v30, 0x2000, v30
	s_waitcnt vmcnt(32)
	v_mul_f32_e32 v13, 0x3fb8aa3b, v62
	v_fma_f32 v14, v62, v19, -v13
	v_rndne_f32_e32 v15, v13
	v_fmac_f32_e32 v14, 0x32a5705f, v62
	v_sub_f32_e32 v13, v13, v15
	v_add_f32_e32 v13, v13, v14
	v_exp_f32_e32 v13, v13
	v_cvt_i32_f32_e32 v14, v15
	v_cmp_ngt_f32_e32 vcc, 0xc2ce8ed0, v62
	v_ldexp_f32 v13, v13, v14
	s_nop 0
	v_cndmask_b32_e32 v13, 0, v13, vcc
	v_cmp_nlt_f32_e32 vcc, 0x42b17218, v62
	s_nop 1
	v_cndmask_b32_e32 v12, v16, v13, vcc
	v_bfe_u32 v24, v20, 16, 1
	v_add3_u32 v24, v20, v24, v17
	v_bfe_u32 v25, v21, 16, 1
	v_lshrrev_b32_e32 v24, 16, v24
	v_add3_u32 v25, v21, v25, v17
	v_and_or_b32 v24, v25, v18, v24
	global_store_dword v27, v24, s[6:7]
	v_add_u32_e32 v27, 0x40000, v27
	v_lshlrev_b32_e32 v22, 16, v42
	v_and_b32_e32 v23, 0xffff0000, v42
	v_fmac_f32_e32 v22, v12, v20
	v_fmac_f32_e32 v23, v12, v21
	v_min_u32_e32 v26, v26, v28
	global_load_dword v42, v26, s[6:7]
	v_add_u32_e32 v26, 0x40000, v26
	v_min_u32_e32 v30, v30, v31
	global_load_dword v62, v30, s[8:9]
	v_add_u32_e32 v30, 0x2000, v30
	s_waitcnt vmcnt(33)
; __device__ __forceinline__ unsigned pack2(float a, float b) { return (unsigned)f2bf(a) | ((unsigned)f2bf(b) << 16); }
; __device__ __forceinline__ float lo16(unsigned v) { return __uint_as_float(v << 16); }
; __device__ __forceinline__ float hi16(unsigned v) { return __uint_as_float(v & 0xffff0000u); }
; __device__ __forceinline__ void phase_scan(const Params& p, unsigned* st, int npairs, int pairs_per_head_shift, int mode) {
;     ...
;   for (int e = blockIdx.x * 256 + tid; e < npairs; e += gridDim.x * 256) {
;     int h = e >> pairs_per_head_shift;
;     float r0 = 0.f, r1 = 0.f;
;     float rdec = 1.f;
;     if (mode == 1) rdec = expf(128.f * logf(1.f - exp2f(-5.f - (float)h)));
;     for (int c0 = 0; c0 < NCH; c0 += 8) {
;       unsigned v[8];
;       float dc[8];
; #pragma unroll
;       for (int i = 0; i < 8; i++) {
;         int c = c0 + i;
;         if (c < NCH) {
;           v[i] = st[(size_t)c * npairs + e];
;           dc[i] = (mode == 0) ? expf(acs[((size_t)c * 16 + h) * 128 + 127]) : rdec;
;         } else { v[i] = 0; dc[i] = 0.f; }
;       }
; #pragma unroll
;       for (int i = 0; i < 8; i++) {
;         int c = c0 + i;
;         if (c < NCH) {
;           *(st + (size_t)c * npairs + e) = pack2(r0, r1);
;           r0 = r0 * dc[i] + lo16(v[i]);
;           r1 = r1 * dc[i] + hi16(v[i]);
;         }
;       }
;     }
;   }
	v_mul_f32_e32 v13, 0x3fb8aa3b, v63
	v_fma_f32 v14, v63, v19, -v13
	v_rndne_f32_e32 v15, v13
	v_fmac_f32_e32 v14, 0x32a5705f, v63
	v_sub_f32_e32 v13, v13, v15
	v_add_f32_e32 v13, v13, v14
	v_exp_f32_e32 v13, v13
	v_cvt_i32_f32_e32 v14, v15
	v_cmp_ngt_f32_e32 vcc, 0xc2ce8ed0, v63
	v_ldexp_f32 v13, v13, v14
	s_nop 0
	v_cndmask_b32_e32 v13, 0, v13, vcc
	v_cmp_nlt_f32_e32 vcc, 0x42b17218, v63
	s_nop 1
	v_cndmask_b32_e32 v12, v16, v13, vcc
	v_bfe_u32 v24, v22, 16, 1
	v_add3_u32 v24, v22, v24, v17
	v_bfe_u32 v25, v23, 16, 1
	v_lshrrev_b32_e32 v24, 16, v24
	v_add3_u32 v25, v23, v25, v17
	v_and_or_b32 v24, v25, v18, v24
	global_store_dword v27, v24, s[6:7]
	v_add_u32_e32 v27, 0x40000, v27
	v_lshlrev_b32_e32 v20, 16, v43
	v_and_b32_e32 v21, 0xffff0000, v43
	v_fmac_f32_e32 v20, v12, v22
	v_fmac_f32_e32 v21, v12, v23
	v_min_u32_e32 v26, v26, v28
	global_load_dword v43, v26, s[6:7]
	v_add_u32_e32 v26, 0x40000, v26
	v_min_u32_e32 v30, v30, v31
	global_load_dword v63, v30, s[8:9]
	v_add_u32_e32 v30, 0x2000, v30
	s_waitcnt vmcnt(34)
	v_mul_f32_e32 v13, 0x3fb8aa3b, v64
	v_fma_f32 v14, v64, v19, -v13
	v_rndne_f32_e32 v15, v13
	v_fmac_f32_e32 v14, 0x32a5705f, v64
	v_sub_f32_e32 v13, v13, v15
	v_add_f32_e32 v13, v13, v14
	v_exp_f32_e32 v13, v13
	v_cvt_i32_f32_e32 v14, v15
	v_cmp_ngt_f32_e32 vcc, 0xc2ce8ed0, v64
	v_ldexp_f32 v13, v13, v14
	s_nop 0
	v_cndmask_b32_e32 v13, 0, v13, vcc
	v_cmp_nlt_f32_e32 vcc, 0x42b17218, v64
	s_nop 1
	v_cndmask_b32_e32 v12, v16, v13, vcc
	v_bfe_u32 v24, v20, 16, 1
	v_add3_u32 v24, v20, v24, v17
	v_bfe_u32 v25, v21, 16, 1
	v_lshrrev_b32_e32 v24, 16, v24
	v_add3_u32 v25, v21, v25, v17
	v_and_or_b32 v24, v25, v18, v24
	global_store_dword v27, v24, s[6:7]
	v_add_u32_e32 v27, 0x40000, v27
	v_lshlrev_b32_e32 v22, 16, v44
	v_and_b32_e32 v23, 0xffff0000, v44
	v_fmac_f32_e32 v22, v12, v20
	v_fmac_f32_e32 v23, v12, v21
	v_min_u32_e32 v26, v26, v28
	global_load_dword v44, v26, s[6:7]
	v_add_u32_e32 v26, 0x40000, v26
	v_min_u32_e32 v30, v30, v31
	global_load_dword v64, v30, s[8:9]
	v_add_u32_e32 v30, 0x2000, v30
	s_waitcnt vmcnt(35)
	v_mul_f32_e32 v13, 0x3fb8aa3b, v65
	v_fma_f32 v14, v65, v19, -v13
	v_rndne_f32_e32 v15, v13
	v_fmac_f32_e32 v14, 0x32a5705f, v65
	v_sub_f32_e32 v13, v13, v15
	v_add_f32_e32 v13, v13, v14
	v_exp_f32_e32 v13, v13
	v_cvt_i32_f32_e32 v14, v15
	v_cmp_ngt_f32_e32 vcc, 0xc2ce8ed0, v65
	v_ldexp_f32 v13, v13, v14
	s_nop 0
	v_cndmask_b32_e32 v13, 0, v13, vcc
	v_cmp_nlt_f32_e32 vcc, 0x42b17218, v65
	s_nop 1
	v_cndmask_b32_e32 v12, v16, v13, vcc
	v_bfe_u32 v24, v22, 16, 1
	v_add3_u32 v24, v22, v24, v17
	v_bfe_u32 v25, v23, 16, 1
	v_lshrrev_b32_e32 v24, 16, v24
	v_add3_u32 v25, v23, v25, v17
	v_and_or_b32 v24, v25, v18, v24
	global_store_dword v27, v24, s[6:7]
	v_add_u32_e32 v27, 0x40000, v27
	v_lshlrev_b32_e32 v20, 16, v45
	v_and_b32_e32 v21, 0xffff0000, v45
	v_fmac_f32_e32 v20, v12, v22
	v_fmac_f32_e32 v21, v12, v23
	v_min_u32_e32 v26, v26, v28
	global_load_dword v45, v26, s[6:7]
	v_add_u32_e32 v26, 0x40000, v26
	v_min_u32_e32 v30, v30, v31
	global_load_dword v65, v30, s[8:9]
	v_add_u32_e32 v30, 0x2000, v30
	s_waitcnt vmcnt(36)
	v_mul_f32_e32 v13, 0x3fb8aa3b, v66
	v_fma_f32 v14, v66, v19, -v13
	v_rndne_f32_e32 v15, v13
	v_fmac_f32_e32 v14, 0x32a5705f, v66
	v_sub_f32_e32 v13, v13, v15
	v_add_f32_e32 v13, v13, v14
	v_exp_f32_e32 v13, v13
	v_cvt_i32_f32_e32 v14, v15
	v_cmp_ngt_f32_e32 vcc, 0xc2ce8ed0, v66
	v_ldexp_f32 v13, v13, v14
	s_nop 0
	v_cndmask_b32_e32 v13, 0, v13, vcc
	v_cmp_nlt_f32_e32 vcc, 0x42b17218, v66
	s_nop 1
	v_cndmask_b32_e32 v12, v16, v13, vcc
	v_bfe_u32 v24, v20, 16, 1
	v_add3_u32 v24, v20, v24, v17
	v_bfe_u32 v25, v21, 16, 1
	v_lshrrev_b32_e32 v24, 16, v24
	v_add3_u32 v25, v21, v25, v17
	v_and_or_b32 v24, v25, v18, v24
	global_store_dword v27, v24, s[6:7]
	v_add_u32_e32 v27, 0x40000, v27
	v_lshlrev_b32_e32 v22, 16, v46
	v_and_b32_e32 v23, 0xffff0000, v46
	v_fmac_f32_e32 v22, v12, v20
	v_fmac_f32_e32 v23, v12, v21
	v_min_u32_e32 v26, v26, v28
	global_load_dword v46, v26, s[6:7]
	v_add_u32_e32 v26, 0x40000, v26
	v_min_u32_e32 v30, v30, v31
	global_load_dword v66, v30, s[8:9]
	v_add_u32_e32 v30, 0x2000, v30
	s_waitcnt vmcnt(37)
	v_mul_f32_e32 v13, 0x3fb8aa3b, v67
	v_fma_f32 v14, v67, v19, -v13
	v_rndne_f32_e32 v15, v13
	v_fmac_f32_e32 v14, 0x32a5705f, v67
	v_sub_f32_e32 v13, v13, v15
	v_add_f32_e32 v13, v13, v14
	v_exp_f32_e32 v13, v13
	v_cvt_i32_f32_e32 v14, v15
	v_cmp_ngt_f32_e32 vcc, 0xc2ce8ed0, v67
	v_ldexp_f32 v13, v13, v14
	s_nop 0
	v_cndmask_b32_e32 v13, 0, v13, vcc
	v_cmp_nlt_f32_e32 vcc, 0x42b17218, v67
	s_nop 1
	v_cndmask_b32_e32 v12, v16, v13, vcc
	v_bfe_u32 v24, v22, 16, 1
	v_add3_u32 v24, v22, v24, v17
	v_bfe_u32 v25, v23, 16, 1
	v_lshrrev_b32_e32 v24, 16, v24
	v_add3_u32 v25, v23, v25, v17
	v_and_or_b32 v24, v25, v18, v24
	global_store_dword v27, v24, s[6:7]
	v_add_u32_e32 v27, 0x40000, v27
	v_lshlrev_b32_e32 v20, 16, v47
	v_and_b32_e32 v21, 0xffff0000, v47
	v_fmac_f32_e32 v20, v12, v22
	v_fmac_f32_e32 v21, v12, v23
	v_min_u32_e32 v26, v26, v28
	global_load_dword v47, v26, s[6:7]
	v_add_u32_e32 v26, 0x40000, v26
	v_min_u32_e32 v30, v30, v31
	global_load_dword v67, v30, s[8:9]
	v_add_u32_e32 v30, 0x2000, v30
	s_waitcnt vmcnt(38)
; __device__ __forceinline__ unsigned pack2(float a, float b) { return (unsigned)f2bf(a) | ((unsigned)f2bf(b) << 16); }
; __device__ __forceinline__ float lo16(unsigned v) { return __uint_as_float(v << 16); }
; __device__ __forceinline__ float hi16(unsigned v) { return __uint_as_float(v & 0xffff0000u); }
; __device__ __forceinline__ void phase_scan(const Params& p, unsigned* st, int npairs, int pairs_per_head_shift, int mode) {
;     ...
;   for (int e = blockIdx.x * 256 + tid; e < npairs; e += gridDim.x * 256) {
;     int h = e >> pairs_per_head_shift;
;     float r0 = 0.f, r1 = 0.f;
;     float rdec = 1.f;
;     if (mode == 1) rdec = expf(128.f * logf(1.f - exp2f(-5.f - (float)h)));
;     for (int c0 = 0; c0 < NCH; c0 += 8) {
;       unsigned v[8];
;       float dc[8];
; #pragma unroll
;       for (int i = 0; i < 8; i++) {
;         int c = c0 + i;
;         if (c < NCH) {
;           v[i] = st[(size_t)c * npairs + e];
;           dc[i] = (mode == 0) ? expf(acs[((size_t)c * 16 + h) * 128 + 127]) : rdec;
;         } else { v[i] = 0; dc[i] = 0.f; }
;       }
; #pragma unroll
;       for (int i = 0; i < 8; i++) {
;         int c = c0 + i;
;         if (c < NCH) {
;           *(st + (size_t)c * npairs + e) = pack2(r0, r1);
;           r0 = r0 * dc[i] + lo16(v[i]);
;           r1 = r1 * dc[i] + hi16(v[i]);
;         }
;       }
;     }
;   }
	v_mul_f32_e32 v13, 0x3fb8aa3b, v68
	v_fma_f32 v14, v68, v19, -v13
	v_rndne_f32_e32 v15, v13
	v_fmac_f32_e32 v14, 0x32a5705f, v68
	v_sub_f32_e32 v13, v13, v15
	v_add_f32_e32 v13, v13, v14
	v_exp_f32_e32 v13, v13
	v_cvt_i32_f32_e32 v14, v15
	v_cmp_ngt_f32_e32 vcc, 0xc2ce8ed0, v68
	v_ldexp_f32 v13, v13, v14
	s_nop 0
	v_cndmask_b32_e32 v13, 0, v13, vcc
	v_cmp_nlt_f32_e32 vcc, 0x42b17218, v68
	s_nop 1
	v_cndmask_b32_e32 v12, v16, v13, vcc
	v_bfe_u32 v24, v20, 16, 1
	v_add3_u32 v24, v20, v24, v17
	v_bfe_u32 v25, v21, 16, 1
	v_lshrrev_b32_e32 v24, 16, v24
	v_add3_u32 v25, v21, v25, v17
	v_and_or_b32 v24, v25, v18, v24
	global_store_dword v27, v24, s[6:7]
	v_add_u32_e32 v27, 0x40000, v27
	v_lshlrev_b32_e32 v22, 16, v48
	v_and_b32_e32 v23, 0xffff0000, v48
	v_fmac_f32_e32 v22, v12, v20
	v_fmac_f32_e32 v23, v12, v21
	v_min_u32_e32 v26, v26, v28
	global_load_dword v48, v26, s[6:7]
	v_add_u32_e32 v26, 0x40000, v26
	v_min_u32_e32 v30, v30, v31
	global_load_dword v68, v30, s[8:9]
	v_add_u32_e32 v30, 0x2000, v30
	s_waitcnt vmcnt(39)
	v_mul_f32_e32 v13, 0x3fb8aa3b, v69
	v_fma_f32 v14, v69, v19, -v13
	v_rndne_f32_e32 v15, v13
	v_fmac_f32_e32 v14, 0x32a5705f, v69
	v_sub_f32_e32 v13, v13, v15
	v_add_f32_e32 v13, v13, v14
	v_exp_f32_e32 v13, v13
	v_cvt_i32_f32_e32 v14, v15
	v_cmp_ngt_f32_e32 vcc, 0xc2ce8ed0, v69
	v_ldexp_f32 v13, v13, v14
	s_nop 0
	v_cndmask_b32_e32 v13, 0, v13, vcc
	v_cmp_nlt_f32_e32 vcc, 0x42b17218, v69
	s_nop 1
	v_cndmask_b32_e32 v12, v16, v13, vcc
	v_bfe_u32 v24, v22, 16, 1
	v_add3_u32 v24, v22, v24, v17
	v_bfe_u32 v25, v23, 16, 1
	v_lshrrev_b32_e32 v24, 16, v24
	v_add3_u32 v25, v23, v25, v17
	v_and_or_b32 v24, v25, v18, v24
	global_store_dword v27, v24, s[6:7]
	v_add_u32_e32 v27, 0x40000, v27
	v_lshlrev_b32_e32 v20, 16, v49
	v_and_b32_e32 v21, 0xffff0000, v49
	v_fmac_f32_e32 v20, v12, v22
	v_fmac_f32_e32 v21, v12, v23
	v_min_u32_e32 v26, v26, v28
	global_load_dword v49, v26, s[6:7]
	v_add_u32_e32 v26, 0x40000, v26
	v_min_u32_e32 v30, v30, v31
	global_load_dword v69, v30, s[8:9]
	v_add_u32_e32 v30, 0x2000, v30
	s_waitcnt vmcnt(40)
	v_mul_f32_e32 v13, 0x3fb8aa3b, v70
	v_fma_f32 v14, v70, v19, -v13
	v_rndne_f32_e32 v15, v13
	v_fmac_f32_e32 v14, 0x32a5705f, v70
	v_sub_f32_e32 v13, v13, v15
	v_add_f32_e32 v13, v13, v14
	v_exp_f32_e32 v13, v13
	v_cvt_i32_f32_e32 v14, v15
	v_cmp_ngt_f32_e32 vcc, 0xc2ce8ed0, v70
	v_ldexp_f32 v13, v13, v14
	s_nop 0
	v_cndmask_b32_e32 v13, 0, v13, vcc
	v_cmp_nlt_f32_e32 vcc, 0x42b17218, v70
	s_nop 1
	v_cndmask_b32_e32 v12, v16, v13, vcc
	v_bfe_u32 v24, v20, 16, 1
	v_add3_u32 v24, v20, v24, v17
	v_bfe_u32 v25, v21, 16, 1
	v_lshrrev_b32_e32 v24, 16, v24
	v_add3_u32 v25, v21, v25, v17
	v_and_or_b32 v24, v25, v18, v24
	global_store_dword v27, v24, s[6:7]
	v_add_u32_e32 v27, 0x40000, v27
	v_lshlrev_b32_e32 v22, 16, v50
	v_and_b32_e32 v23, 0xffff0000, v50
	v_fmac_f32_e32 v22, v12, v20
	v_fmac_f32_e32 v23, v12, v21
	v_min_u32_e32 v26, v26, v28
	global_load_dword v50, v26, s[6:7]
	v_add_u32_e32 v26, 0x40000, v26
	v_min_u32_e32 v30, v30, v31
	global_load_dword v70, v30, s[8:9]
	v_add_u32_e32 v30, 0x2000, v30
	s_waitcnt vmcnt(41)
	v_mul_f32_e32 v13, 0x3fb8aa3b, v71
	v_fma_f32 v14, v71, v19, -v13
	v_rndne_f32_e32 v15, v13
	v_fmac_f32_e32 v14, 0x32a5705f, v71
	v_sub_f32_e32 v13, v13, v15
	v_add_f32_e32 v13, v13, v14
	v_exp_f32_e32 v13, v13
	v_cvt_i32_f32_e32 v14, v15
	v_cmp_ngt_f32_e32 vcc, 0xc2ce8ed0, v71
	v_ldexp_f32 v13, v13, v14
	s_nop 0
	v_cndmask_b32_e32 v13, 0, v13, vcc
	v_cmp_nlt_f32_e32 vcc, 0x42b17218, v71
	s_nop 1
	v_cndmask_b32_e32 v12, v16, v13, vcc
	v_bfe_u32 v24, v22, 16, 1
	v_add3_u32 v24, v22, v24, v17
	v_bfe_u32 v25, v23, 16, 1
	v_lshrrev_b32_e32 v24, 16, v24
	v_add3_u32 v25, v23, v25, v17
	v_and_or_b32 v24, v25, v18, v24
	global_store_dword v27, v24, s[6:7]
	v_add_u32_e32 v27, 0x40000, v27
	v_lshlrev_b32_e32 v20, 16, v51
	v_and_b32_e32 v21, 0xffff0000, v51
	v_fmac_f32_e32 v20, v12, v22
	v_fmac_f32_e32 v21, v12, v23
	v_min_u32_e32 v26, v26, v28
	global_load_dword v51, v26, s[6:7]
	v_add_u32_e32 v26, 0x40000, v26
	v_min_u32_e32 v30, v30, v31
	global_load_dword v71, v30, s[8:9]
	v_add_u32_e32 v30, 0x2000, v30
	s_waitcnt vmcnt(42)
	v_mul_f32_e32 v13, 0x3fb8aa3b, v72
	v_fma_f32 v14, v72, v19, -v13
	v_rndne_f32_e32 v15, v13
	v_fmac_f32_e32 v14, 0x32a5705f, v72
	v_sub_f32_e32 v13, v13, v15
	v_add_f32_e32 v13, v13, v14
	v_exp_f32_e32 v13, v13
	v_cvt_i32_f32_e32 v14, v15
	v_cmp_ngt_f32_e32 vcc, 0xc2ce8ed0, v72
	v_ldexp_f32 v13, v13, v14
	s_nop 0
	v_cndmask_b32_e32 v13, 0, v13, vcc
	v_cmp_nlt_f32_e32 vcc, 0x42b17218, v72
	s_nop 1
	v_cndmask_b32_e32 v12, v16, v13, vcc
	v_bfe_u32 v24, v20, 16, 1
	v_add3_u32 v24, v20, v24, v17
	v_bfe_u32 v25, v21, 16, 1
	v_lshrrev_b32_e32 v24, 16, v24
	v_add3_u32 v25, v21, v25, v17
	v_and_or_b32 v24, v25, v18, v24
	global_store_dword v27, v24, s[6:7]
	v_add_u32_e32 v27, 0x40000, v27
	v_lshlrev_b32_e32 v22, 16, v52
	v_and_b32_e32 v23, 0xffff0000, v52
	v_fmac_f32_e32 v22, v12, v20
	v_fmac_f32_e32 v23, v12, v21
	v_min_u32_e32 v26, v26, v28
	global_load_dword v52, v26, s[6:7]
	v_add_u32_e32 v26, 0x40000, v26
	v_min_u32_e32 v30, v30, v31
	global_load_dword v72, v30, s[8:9]
	v_add_u32_e32 v30, 0x2000, v30
	s_waitcnt vmcnt(43)
; __device__ __forceinline__ unsigned pack2(float a, float b) { return (unsigned)f2bf(a) | ((unsigned)f2bf(b) << 16); }
; __device__ __forceinline__ float lo16(unsigned v) { return __uint_as_float(v << 16); }
; __device__ __forceinline__ float hi16(unsigned v) { return __uint_as_float(v & 0xffff0000u); }
; __device__ __forceinline__ void phase_scan(const Params& p, unsigned* st, int npairs, int pairs_per_head_shift, int mode) {
;     ...
;   for (int e = blockIdx.x * 256 + tid; e < npairs; e += gridDim.x * 256) {
;     int h = e >> pairs_per_head_shift;
;     float r0 = 0.f, r1 = 0.f;
;     float rdec = 1.f;
;     if (mode == 1) rdec = expf(128.f * logf(1.f - exp2f(-5.f - (float)h)));
;     for (int c0 = 0; c0 < NCH; c0 += 8) {
;       unsigned v[8];
;       float dc[8];
; #pragma unroll
;       for (int i = 0; i < 8; i++) {
;         int c = c0 + i;
;         if (c < NCH) {
;           v[i] = st[(size_t)c * npairs + e];
;           dc[i] = (mode == 0) ? expf(acs[((size_t)c * 16 + h) * 128 + 127]) : rdec;
;         } else { v[i] = 0; dc[i] = 0.f; }
;       }
; #pragma unroll
;       for (int i = 0; i < 8; i++) {
;         int c = c0 + i;
;         if (c < NCH) {
;           *(st + (size_t)c * npairs + e) = pack2(r0, r1);
;           r0 = r0 * dc[i] + lo16(v[i]);
;           r1 = r1 * dc[i] + hi16(v[i]);
;         }
;       }
;     }
;   }
	v_mul_f32_e32 v13, 0x3fb8aa3b, v73
	v_fma_f32 v14, v73, v19, -v13
	v_rndne_f32_e32 v15, v13
	v_fmac_f32_e32 v14, 0x32a5705f, v73
	v_sub_f32_e32 v13, v13, v15
	v_add_f32_e32 v13, v13, v14
	v_exp_f32_e32 v13, v13
	v_cvt_i32_f32_e32 v14, v15
	v_cmp_ngt_f32_e32 vcc, 0xc2ce8ed0, v73
	v_ldexp_f32 v13, v13, v14
	s_nop 0
	v_cndmask_b32_e32 v13, 0, v13, vcc
	v_cmp_nlt_f32_e32 vcc, 0x42b17218, v73
	s_nop 1
	v_cndmask_b32_e32 v12, v16, v13, vcc
	v_bfe_u32 v24, v22, 16, 1
	v_add3_u32 v24, v22, v24, v17
	v_bfe_u32 v25, v23, 16, 1
	v_lshrrev_b32_e32 v24, 16, v24
	v_add3_u32 v25, v23, v25, v17
	v_and_or_b32 v24, v25, v18, v24
	global_store_dword v27, v24, s[6:7]
	v_add_u32_e32 v27, 0x40000, v27
	v_lshlrev_b32_e32 v20, 16, v53
	v_and_b32_e32 v21, 0xffff0000, v53
	v_fmac_f32_e32 v20, v12, v22
	v_fmac_f32_e32 v21, v12, v23
	v_min_u32_e32 v26, v26, v28
	global_load_dword v53, v26, s[6:7]
	v_add_u32_e32 v26, 0x40000, v26
	v_min_u32_e32 v30, v30, v31
	global_load_dword v73, v30, s[8:9]
	v_add_u32_e32 v30, 0x2000, v30
	s_waitcnt vmcnt(44)
	v_mul_f32_e32 v13, 0x3fb8aa3b, v74
	v_fma_f32 v14, v74, v19, -v13
	v_rndne_f32_e32 v15, v13
	v_fmac_f32_e32 v14, 0x32a5705f, v74
	v_sub_f32_e32 v13, v13, v15
	v_add_f32_e32 v13, v13, v14
	v_exp_f32_e32 v13, v13
	v_cvt_i32_f32_e32 v14, v15
	v_cmp_ngt_f32_e32 vcc, 0xc2ce8ed0, v74
	v_ldexp_f32 v13, v13, v14
	s_nop 0
	v_cndmask_b32_e32 v13, 0, v13, vcc
	v_cmp_nlt_f32_e32 vcc, 0x42b17218, v74
	s_nop 1
	v_cndmask_b32_e32 v12, v16, v13, vcc
	v_bfe_u32 v24, v20, 16, 1
	v_add3_u32 v24, v20, v24, v17
	v_bfe_u32 v25, v21, 16, 1
	v_lshrrev_b32_e32 v24, 16, v24
	v_add3_u32 v25, v21, v25, v17
	v_and_or_b32 v24, v25, v18, v24
	global_store_dword v27, v24, s[6:7]
	v_add_u32_e32 v27, 0x40000, v27
	v_lshlrev_b32_e32 v22, 16, v54
	v_and_b32_e32 v23, 0xffff0000, v54
	v_fmac_f32_e32 v22, v12, v20
	v_fmac_f32_e32 v23, v12, v21
	v_min_u32_e32 v26, v26, v28
	global_load_dword v54, v26, s[6:7]
	v_add_u32_e32 v26, 0x40000, v26
	v_min_u32_e32 v30, v30, v31
	global_load_dword v74, v30, s[8:9]
	v_add_u32_e32 v30, 0x2000, v30
	s_waitcnt vmcnt(45)
	v_mul_f32_e32 v13, 0x3fb8aa3b, v75
	v_fma_f32 v14, v75, v19, -v13
	v_rndne_f32_e32 v15, v13
	v_fmac_f32_e32 v14, 0x32a5705f, v75
	v_sub_f32_e32 v13, v13, v15
	v_add_f32_e32 v13, v13, v14
	v_exp_f32_e32 v13, v13
	v_cvt_i32_f32_e32 v14, v15
	v_cmp_ngt_f32_e32 vcc, 0xc2ce8ed0, v75
	v_ldexp_f32 v13, v13, v14
	s_nop 0
	v_cndmask_b32_e32 v13, 0, v13, vcc
	v_cmp_nlt_f32_e32 vcc, 0x42b17218, v75
	s_nop 1
	v_cndmask_b32_e32 v12, v16, v13, vcc
	v_bfe_u32 v24, v22, 16, 1
	v_add3_u32 v24, v22, v24, v17
	v_bfe_u32 v25, v23, 16, 1
	v_lshrrev_b32_e32 v24, 16, v24
	v_add3_u32 v25, v23, v25, v17
	v_and_or_b32 v24, v25, v18, v24
	global_store_dword v27, v24, s[6:7]
	v_add_u32_e32 v27, 0x40000, v27
	v_lshlrev_b32_e32 v20, 16, v55
	v_and_b32_e32 v21, 0xffff0000, v55
	v_fmac_f32_e32 v20, v12, v22
	v_fmac_f32_e32 v21, v12, v23
	v_min_u32_e32 v26, v26, v28
	global_load_dword v55, v26, s[6:7]
	v_add_u32_e32 v26, 0x40000, v26
	v_min_u32_e32 v30, v30, v31
	global_load_dword v75, v30, s[8:9]
	v_add_u32_e32 v30, 0x2000, v30
	s_mov_b32 m0, 7
.Lscan_ssd0_loop:
	s_waitcnt vmcnt(45)
	v_mul_f32_e32 v13, 0x3fb8aa3b, v60
	v_fma_f32 v14, v60, v19, -v13
	v_rndne_f32_e32 v15, v13
	v_fmac_f32_e32 v14, 0x32a5705f, v60
	v_sub_f32_e32 v13, v13, v15
	v_add_f32_e32 v13, v13, v14
	v_exp_f32_e32 v13, v13
	v_cvt_i32_f32_e32 v14, v15
	v_cmp_ngt_f32_e32 vcc, 0xc2ce8ed0, v60
	v_ldexp_f32 v13, v13, v14
	s_nop 0
	v_cndmask_b32_e32 v13, 0, v13, vcc
	v_cmp_nlt_f32_e32 vcc, 0x42b17218, v60
	s_nop 1
	v_cndmask_b32_e32 v12, v16, v13, vcc
	v_bfe_u32 v24, v20, 16, 1
	v_add3_u32 v24, v20, v24, v17
	v_bfe_u32 v25, v21, 16, 1
	v_lshrrev_b32_e32 v24, 16, v24
	v_add3_u32 v25, v21, v25, v17
	v_and_or_b32 v24, v25, v18, v24
	global_store_dword v27, v24, s[6:7]
	v_add_u32_e32 v27, 0x40000, v27
	v_lshlrev_b32_e32 v22, 16, v40
	v_and_b32_e32 v23, 0xffff0000, v40
	v_fmac_f32_e32 v22, v12, v20
	v_fmac_f32_e32 v23, v12, v21
	v_min_u32_e32 v26, v26, v28
	global_load_dword v40, v26, s[6:7]
	v_add_u32_e32 v26, 0x40000, v26
	v_min_u32_e32 v30, v30, v31
	global_load_dword v60, v30, s[8:9]
	v_add_u32_e32 v30, 0x2000, v30
	s_waitcnt vmcnt(45)
	v_mul_f32_e32 v13, 0x3fb8aa3b, v61
	v_fma_f32 v14, v61, v19, -v13
	v_rndne_f32_e32 v15, v13
	v_fmac_f32_e32 v14, 0x32a5705f, v61
	v_sub_f32_e32 v13, v13, v15
	v_add_f32_e32 v13, v13, v14
	v_exp_f32_e32 v13, v13
	v_cvt_i32_f32_e32 v14, v15
	v_cmp_ngt_f32_e32 vcc, 0xc2ce8ed0, v61
	v_ldexp_f32 v13, v13, v14
	s_nop 0
	v_cndmask_b32_e32 v13, 0, v13, vcc
	v_cmp_nlt_f32_e32 vcc, 0x42b17218, v61
	s_nop 1
	v_cndmask_b32_e32 v12, v16, v13, vcc
	v_bfe_u32 v24, v22, 16, 1
	v_add3_u32 v24, v22, v24, v17
	v_bfe_u32 v25, v23, 16, 1
	v_lshrrev_b32_e32 v24, 16, v24
	v_add3_u32 v25, v23, v25, v17
	v_and_or_b32 v24, v25, v18, v24
	global_store_dword v27, v24, s[6:7]
	v_add_u32_e32 v27, 0x40000, v27
	v_lshlrev_b32_e32 v20, 16, v41
	v_and_b32_e32 v21, 0xffff0000, v41
	v_fmac_f32_e32 v20, v12, v22
	v_fmac_f32_e32 v21, v12, v23
	v_min_u32_e32 v26, v26, v28
	global_load_dword v41, v26, s[6:7]
	v_add_u32_e32 v26, 0x40000, v26
	v_min_u32_e32 v30, v30, v31
	global_load_dword v61, v30, s[8:9]
	v_add_u32_e32 v30, 0x2000, v30
	s_waitcnt vmcnt(45)
; __device__ __forceinline__ unsigned pack2(float a, float b) { return (unsigned)f2bf(a) | ((unsigned)f2bf(b) << 16); }
; __device__ __forceinline__ float lo16(unsigned v) { return __uint_as_float(v << 16); }
; __device__ __forceinline__ float hi16(unsigned v) { return __uint_as_float(v & 0xffff0000u); }
; __device__ __forceinline__ void phase_scan(const Params& p, unsigned* st, int npairs, int pairs_per_head_shift, int mode) {
;     ...
;   for (int e = blockIdx.x * 256 + tid; e < npairs; e += gridDim.x * 256) {
;     int h = e >> pairs_per_head_shift;
;     float r0 = 0.f, r1 = 0.f;
;     float rdec = 1.f;
;     if (mode == 1) rdec = expf(128.f * logf(1.f - exp2f(-5.f - (float)h)));
;     for (int c0 = 0; c0 < NCH; c0 += 8) {
;       unsigned v[8];
;       float dc[8];
; #pragma unroll
;       for (int i = 0; i < 8; i++) {
;         int c = c0 + i;
;         if (c < NCH) {
;           v[i] = st[(size_t)c * npairs + e];
;           dc[i] = (mode == 0) ? expf(acs[((size_t)c * 16 + h) * 128 + 127]) : rdec;
;         } else { v[i] = 0; dc[i] = 0.f; }
;       }
; #pragma unroll
;       for (int i = 0; i < 8; i++) {
;         int c = c0 + i;
;         if (c < NCH) {
;           *(st + (size_t)c * npairs + e) = pack2(r0, r1);
;           r0 = r0 * dc[i] + lo16(v[i]);
;           r1 = r1 * dc[i] + hi16(v[i]);
;         }
;       }
;     }
;   }
	v_mul_f32_e32 v13, 0x3fb8aa3b, v62
	v_fma_f32 v14, v62, v19, -v13
	v_rndne_f32_e32 v15, v13
	v_fmac_f32_e32 v14, 0x32a5705f, v62
	v_sub_f32_e32 v13, v13, v15
	v_add_f32_e32 v13, v13, v14
	v_exp_f32_e32 v13, v13
	v_cvt_i32_f32_e32 v14, v15
	v_cmp_ngt_f32_e32 vcc, 0xc2ce8ed0, v62
	v_ldexp_f32 v13, v13, v14
	s_nop 0
	v_cndmask_b32_e32 v13, 0, v13, vcc
	v_cmp_nlt_f32_e32 vcc, 0x42b17218, v62
	s_nop 1
	v_cndmask_b32_e32 v12, v16, v13, vcc
	v_bfe_u32 v24, v20, 16, 1
	v_add3_u32 v24, v20, v24, v17
	v_bfe_u32 v25, v21, 16, 1
	v_lshrrev_b32_e32 v24, 16, v24
	v_add3_u32 v25, v21, v25, v17
	v_and_or_b32 v24, v25, v18, v24
	global_store_dword v27, v24, s[6:7]
	v_add_u32_e32 v27, 0x40000, v27
	v_lshlrev_b32_e32 v22, 16, v42
	v_and_b32_e32 v23, 0xffff0000, v42
	v_fmac_f32_e32 v22, v12, v20
	v_fmac_f32_e32 v23, v12, v21
	v_min_u32_e32 v26, v26, v28
	global_load_dword v42, v26, s[6:7]
	v_add_u32_e32 v26, 0x40000, v26
	v_min_u32_e32 v30, v30, v31
	global_load_dword v62, v30, s[8:9]
	v_add_u32_e32 v30, 0x2000, v30
	s_waitcnt vmcnt(45)
	v_mul_f32_e32 v13, 0x3fb8aa3b, v63
	v_fma_f32 v14, v63, v19, -v13
	v_rndne_f32_e32 v15, v13
	v_fmac_f32_e32 v14, 0x32a5705f, v63
	v_sub_f32_e32 v13, v13, v15
	v_add_f32_e32 v13, v13, v14
	v_exp_f32_e32 v13, v13
	v_cvt_i32_f32_e32 v14, v15
	v_cmp_ngt_f32_e32 vcc, 0xc2ce8ed0, v63
	v_ldexp_f32 v13, v13, v14
	s_nop 0
	v_cndmask_b32_e32 v13, 0, v13, vcc
	v_cmp_nlt_f32_e32 vcc, 0x42b17218, v63
	s_nop 1
	v_cndmask_b32_e32 v12, v16, v13, vcc
	v_bfe_u32 v24, v22, 16, 1
	v_add3_u32 v24, v22, v24, v17
	v_bfe_u32 v25, v23, 16, 1
	v_lshrrev_b32_e32 v24, 16, v24
	v_add3_u32 v25, v23, v25, v17
	v_and_or_b32 v24, v25, v18, v24
	global_store_dword v27, v24, s[6:7]
	v_add_u32_e32 v27, 0x40000, v27
	v_lshlrev_b32_e32 v20, 16, v43
	v_and_b32_e32 v21, 0xffff0000, v43
	v_fmac_f32_e32 v20, v12, v22
	v_fmac_f32_e32 v21, v12, v23
	v_min_u32_e32 v26, v26, v28
	global_load_dword v43, v26, s[6:7]
	v_add_u32_e32 v26, 0x40000, v26
	v_min_u32_e32 v30, v30, v31
	global_load_dword v63, v30, s[8:9]
	v_add_u32_e32 v30, 0x2000, v30
	s_waitcnt vmcnt(45)
	v_mul_f32_e32 v13, 0x3fb8aa3b, v64
	v_fma_f32 v14, v64, v19, -v13
	v_rndne_f32_e32 v15, v13
	v_fmac_f32_e32 v14, 0x32a5705f, v64
	v_sub_f32_e32 v13, v13, v15
	v_add_f32_e32 v13, v13, v14
	v_exp_f32_e32 v13, v13
	v_cvt_i32_f32_e32 v14, v15
	v_cmp_ngt_f32_e32 vcc, 0xc2ce8ed0, v64
	v_ldexp_f32 v13, v13, v14
	s_nop 0
	v_cndmask_b32_e32 v13, 0, v13, vcc
	v_cmp_nlt_f32_e32 vcc, 0x42b17218, v64
	s_nop 1
	v_cndmask_b32_e32 v12, v16, v13, vcc
	v_bfe_u32 v24, v20, 16, 1
	v_add3_u32 v24, v20, v24, v17
	v_bfe_u32 v25, v21, 16, 1
	v_lshrrev_b32_e32 v24, 16, v24
	v_add3_u32 v25, v21, v25, v17
	v_and_or_b32 v24, v25, v18, v24
	global_store_dword v27, v24, s[6:7]
	v_add_u32_e32 v27, 0x40000, v27
	v_lshlrev_b32_e32 v22, 16, v44
	v_and_b32_e32 v23, 0xffff0000, v44
	v_fmac_f32_e32 v22, v12, v20
	v_fmac_f32_e32 v23, v12, v21
	v_min_u32_e32 v26, v26, v28
	global_load_dword v44, v26, s[6:7]
	v_add_u32_e32 v26, 0x40000, v26
	v_min_u32_e32 v30, v30, v31
	global_load_dword v64, v30, s[8:9]
	v_add_u32_e32 v30, 0x2000, v30
	s_waitcnt vmcnt(45)
	v_mul_f32_e32 v13, 0x3fb8aa3b, v65
	v_fma_f32 v14, v65, v19, -v13
	v_rndne_f32_e32 v15, v13
	v_fmac_f32_e32 v14, 0x32a5705f, v65
	v_sub_f32_e32 v13, v13, v15
	v_add_f32_e32 v13, v13, v14
	v_exp_f32_e32 v13, v13
	v_cvt_i32_f32_e32 v14, v15
	v_cmp_ngt_f32_e32 vcc, 0xc2ce8ed0, v65
	v_ldexp_f32 v13, v13, v14
	s_nop 0
	v_cndmask_b32_e32 v13, 0, v13, vcc
	v_cmp_nlt_f32_e32 vcc, 0x42b17218, v65
	s_nop 1
	v_cndmask_b32_e32 v12, v16, v13, vcc
	v_bfe_u32 v24, v22, 16, 1
	v_add3_u32 v24, v22, v24, v17
	v_bfe_u32 v25, v23, 16, 1
	v_lshrrev_b32_e32 v24, 16, v24
	v_add3_u32 v25, v23, v25, v17
	v_and_or_b32 v24, v25, v18, v24
	global_store_dword v27, v24, s[6:7]
	v_add_u32_e32 v27, 0x40000, v27
	v_lshlrev_b32_e32 v20, 16, v45
	v_and_b32_e32 v21, 0xffff0000, v45
	v_fmac_f32_e32 v20, v12, v22
	v_fmac_f32_e32 v21, v12, v23
	v_min_u32_e32 v26, v26, v28
	global_load_dword v45, v26, s[6:7]
	v_add_u32_e32 v26, 0x40000, v26
	v_min_u32_e32 v30, v30, v31
	global_load_dword v65, v30, s[8:9]
	v_add_u32_e32 v30, 0x2000, v30
	s_waitcnt vmcnt(45)
	v_mul_f32_e32 v13, 0x3fb8aa3b, v66
	v_fma_f32 v14, v66, v19, -v13
	v_rndne_f32_e32 v15, v13
	v_fmac_f32_e32 v14, 0x32a5705f, v66
	v_sub_f32_e32 v13, v13, v15
	v_add_f32_e32 v13, v13, v14
	v_exp_f32_e32 v13, v13
	v_cvt_i32_f32_e32 v14, v15
	v_cmp_ngt_f32_e32 vcc, 0xc2ce8ed0, v66
	v_ldexp_f32 v13, v13, v14
	s_nop 0
	v_cndmask_b32_e32 v13, 0, v13, vcc
	v_cmp_nlt_f32_e32 vcc, 0x42b17218, v66
	s_nop 1
	v_cndmask_b32_e32 v12, v16, v13, vcc
	v_bfe_u32 v24, v20, 16, 1
	v_add3_u32 v24, v20, v24, v17
	v_bfe_u32 v25, v21, 16, 1
	v_lshrrev_b32_e32 v24, 16, v24
	v_add3_u32 v25, v21, v25, v17
	v_and_or_b32 v24, v25, v18, v24
	global_store_dword v27, v24, s[6:7]
	v_add_u32_e32 v27, 0x40000, v27
	v_lshlrev_b32_e32 v22, 16, v46
	v_and_b32_e32 v23, 0xffff0000, v46
	v_fmac_f32_e32 v22, v12, v20
	v_fmac_f32_e32 v23, v12, v21
	v_min_u32_e32 v26, v26, v28
	global_load_dword v46, v26, s[6:7]
	v_add_u32_e32 v26, 0x40000, v26
	v_min_u32_e32 v30, v30, v31
	global_load_dword v66, v30, s[8:9]
	v_add_u32_e32 v30, 0x2000, v30
	s_waitcnt vmcnt(45)
; __device__ __forceinline__ unsigned pack2(float a, float b) { return (unsigned)f2bf(a) | ((unsigned)f2bf(b) << 16); }
; __device__ __forceinline__ float lo16(unsigned v) { return __uint_as_float(v << 16); }
; __device__ __forceinline__ float hi16(unsigned v) { return __uint_as_float(v & 0xffff0000u); }
; __device__ __forceinline__ void phase_scan(const Params& p, unsigned* st, int npairs, int pairs_per_head_shift, int mode) {
;     ...
;   for (int e = blockIdx.x * 256 + tid; e < npairs; e += gridDim.x * 256) {
;     int h = e >> pairs_per_head_shift;
;     float r0 = 0.f, r1 = 0.f;
;     float rdec = 1.f;
;     if (mode == 1) rdec = expf(128.f * logf(1.f - exp2f(-5.f - (float)h)));
;     for (int c0 = 0; c0 < NCH; c0 += 8) {
;       unsigned v[8];
;       float dc[8];
; #pragma unroll
;       for (int i = 0; i < 8; i++) {
;         int c = c0 + i;
;         if (c < NCH) {
;           v[i] = st[(size_t)c * npairs + e];
;           dc[i] = (mode == 0) ? expf(acs[((size_t)c * 16 + h) * 128 + 127]) : rdec;
;         } else { v[i] = 0; dc[i] = 0.f; }
;       }
; #pragma unroll
;       for (int i = 0; i < 8; i++) {
;         int c = c0 + i;
;         if (c < NCH) {
;           *(st + (size_t)c * npairs + e) = pack2(r0, r1);
;           r0 = r0 * dc[i] + lo16(v[i]);
;           r1 = r1 * dc[i] + hi16(v[i]);
;         }
;       }
;     }
;   }
	v_mul_f32_e32 v13, 0x3fb8aa3b, v67
	v_fma_f32 v14, v67, v19, -v13
	v_rndne_f32_e32 v15, v13
	v_fmac_f32_e32 v14, 0x32a5705f, v67
	v_sub_f32_e32 v13, v13, v15
	v_add_f32_e32 v13, v13, v14
	v_exp_f32_e32 v13, v13
	v_cvt_i32_f32_e32 v14, v15
	v_cmp_ngt_f32_e32 vcc, 0xc2ce8ed0, v67
	v_ldexp_f32 v13, v13, v14
	s_nop 0
	v_cndmask_b32_e32 v13, 0, v13, vcc
	v_cmp_nlt_f32_e32 vcc, 0x42b17218, v67
	s_nop 1
	v_cndmask_b32_e32 v12, v16, v13, vcc
	v_bfe_u32 v24, v22, 16, 1
	v_add3_u32 v24, v22, v24, v17
	v_bfe_u32 v25, v23, 16, 1
	v_lshrrev_b32_e32 v24, 16, v24
	v_add3_u32 v25, v23, v25, v17
	v_and_or_b32 v24, v25, v18, v24
	global_store_dword v27, v24, s[6:7]
	v_add_u32_e32 v27, 0x40000, v27
	v_lshlrev_b32_e32 v20, 16, v47
	v_and_b32_e32 v21, 0xffff0000, v47
	v_fmac_f32_e32 v20, v12, v22
	v_fmac_f32_e32 v21, v12, v23
	v_min_u32_e32 v26, v26, v28
	global_load_dword v47, v26, s[6:7]
	v_add_u32_e32 v26, 0x40000, v26
	v_min_u32_e32 v30, v30, v31
	global_load_dword v67, v30, s[8:9]
	v_add_u32_e32 v30, 0x2000, v30
	s_waitcnt vmcnt(45)
	v_mul_f32_e32 v13, 0x3fb8aa3b, v68
	v_fma_f32 v14, v68, v19, -v13
	v_rndne_f32_e32 v15, v13
	v_fmac_f32_e32 v14, 0x32a5705f, v68
	v_sub_f32_e32 v13, v13, v15
	v_add_f32_e32 v13, v13, v14
	v_exp_f32_e32 v13, v13
	v_cvt_i32_f32_e32 v14, v15
	v_cmp_ngt_f32_e32 vcc, 0xc2ce8ed0, v68
	v_ldexp_f32 v13, v13, v14
	s_nop 0
	v_cndmask_b32_e32 v13, 0, v13, vcc
	v_cmp_nlt_f32_e32 vcc, 0x42b17218, v68
	s_nop 1
	v_cndmask_b32_e32 v12, v16, v13, vcc
	v_bfe_u32 v24, v20, 16, 1
	v_add3_u32 v24, v20, v24, v17
	v_bfe_u32 v25, v21, 16, 1
	v_lshrrev_b32_e32 v24, 16, v24
	v_add3_u32 v25, v21, v25, v17
	v_and_or_b32 v24, v25, v18, v24
	global_store_dword v27, v24, s[6:7]
	v_add_u32_e32 v27, 0x40000, v27
	v_lshlrev_b32_e32 v22, 16, v48
	v_and_b32_e32 v23, 0xffff0000, v48
	v_fmac_f32_e32 v22, v12, v20
	v_fmac_f32_e32 v23, v12, v21
	v_min_u32_e32 v26, v26, v28
	global_load_dword v48, v26, s[6:7]
	v_add_u32_e32 v26, 0x40000, v26
	v_min_u32_e32 v30, v30, v31
	global_load_dword v68, v30, s[8:9]
	v_add_u32_e32 v30, 0x2000, v30
	s_waitcnt vmcnt(45)
	v_mul_f32_e32 v13, 0x3fb8aa3b, v69
	v_fma_f32 v14, v69, v19, -v13
	v_rndne_f32_e32 v15, v13
	v_fmac_f32_e32 v14, 0x32a5705f, v69
	v_sub_f32_e32 v13, v13, v15
	v_add_f32_e32 v13, v13, v14
	v_exp_f32_e32 v13, v13
	v_cvt_i32_f32_e32 v14, v15
	v_cmp_ngt_f32_e32 vcc, 0xc2ce8ed0, v69
	v_ldexp_f32 v13, v13, v14
	s_nop 0
	v_cndmask_b32_e32 v13, 0, v13, vcc
	v_cmp_nlt_f32_e32 vcc, 0x42b17218, v69
	s_nop 1
	v_cndmask_b32_e32 v12, v16, v13, vcc
	v_bfe_u32 v24, v22, 16, 1
	v_add3_u32 v24, v22, v24, v17
	v_bfe_u32 v25, v23, 16, 1
	v_lshrrev_b32_e32 v24, 16, v24
	v_add3_u32 v25, v23, v25, v17
	v_and_or_b32 v24, v25, v18, v24
	global_store_dword v27, v24, s[6:7]
	v_add_u32_e32 v27, 0x40000, v27
	v_lshlrev_b32_e32 v20, 16, v49
	v_and_b32_e32 v21, 0xffff0000, v49
	v_fmac_f32_e32 v20, v12, v22
	v_fmac_f32_e32 v21, v12, v23
	v_min_u32_e32 v26, v26, v28
	global_load_dword v49, v26, s[6:7]
	v_add_u32_e32 v26, 0x40000, v26
	v_min_u32_e32 v30, v30, v31
	global_load_dword v69, v30, s[8:9]
	v_add_u32_e32 v30, 0x2000, v30
	s_waitcnt vmcnt(45)
	v_mul_f32_e32 v13, 0x3fb8aa3b, v70
	v_fma_f32 v14, v70, v19, -v13
	v_rndne_f32_e32 v15, v13
	v_fmac_f32_e32 v14, 0x32a5705f, v70
	v_sub_f32_e32 v13, v13, v15
	v_add_f32_e32 v13, v13, v14
	v_exp_f32_e32 v13, v13
	v_cvt_i32_f32_e32 v14, v15
	v_cmp_ngt_f32_e32 vcc, 0xc2ce8ed0, v70
	v_ldexp_f32 v13, v13, v14
	s_nop 0
	v_cndmask_b32_e32 v13, 0, v13, vcc
	v_cmp_nlt_f32_e32 vcc, 0x42b17218, v70
	s_nop 1
	v_cndmask_b32_e32 v12, v16, v13, vcc
	v_bfe_u32 v24, v20, 16, 1
	v_add3_u32 v24, v20, v24, v17
	v_bfe_u32 v25, v21, 16, 1
	v_lshrrev_b32_e32 v24, 16, v24
	v_add3_u32 v25, v21, v25, v17
	v_and_or_b32 v24, v25, v18, v24
	global_store_dword v27, v24, s[6:7]
	v_add_u32_e32 v27, 0x40000, v27
	v_lshlrev_b32_e32 v22, 16, v50
	v_and_b32_e32 v23, 0xffff0000, v50
	v_fmac_f32_e32 v22, v12, v20
	v_fmac_f32_e32 v23, v12, v21
	v_min_u32_e32 v26, v26, v28
	global_load_dword v50, v26, s[6:7]
	v_add_u32_e32 v26, 0x40000, v26
	v_min_u32_e32 v30, v30, v31
	global_load_dword v70, v30, s[8:9]
	v_add_u32_e32 v30, 0x2000, v30
	s_waitcnt vmcnt(45)
	v_mul_f32_e32 v13, 0x3fb8aa3b, v71
	v_fma_f32 v14, v71, v19, -v13
	v_rndne_f32_e32 v15, v13
	v_fmac_f32_e32 v14, 0x32a5705f, v71
	v_sub_f32_e32 v13, v13, v15
	v_add_f32_e32 v13, v13, v14
	v_exp_f32_e32 v13, v13
	v_cvt_i32_f32_e32 v14, v15
	v_cmp_ngt_f32_e32 vcc, 0xc2ce8ed0, v71
	v_ldexp_f32 v13, v13, v14
	s_nop 0
	v_cndmask_b32_e32 v13, 0, v13, vcc
	v_cmp_nlt_f32_e32 vcc, 0x42b17218, v71
	s_nop 1
	v_cndmask_b32_e32 v12, v16, v13, vcc
	v_bfe_u32 v24, v22, 16, 1
	v_add3_u32 v24, v22, v24, v17
	v_bfe_u32 v25, v23, 16, 1
	v_lshrrev_b32_e32 v24, 16, v24
	v_add3_u32 v25, v23, v25, v17
	v_and_or_b32 v24, v25, v18, v24
	global_store_dword v27, v24, s[6:7]
	v_add_u32_e32 v27, 0x40000, v27
	v_lshlrev_b32_e32 v20, 16, v51
	v_and_b32_e32 v21, 0xffff0000, v51
	v_fmac_f32_e32 v20, v12, v22
	v_fmac_f32_e32 v21, v12, v23
	v_min_u32_e32 v26, v26, v28
	global_load_dword v51, v26, s[6:7]
	v_add_u32_e32 v26, 0x40000, v26
	v_min_u32_e32 v30, v30, v31
	global_load_dword v71, v30, s[8:9]
	v_add_u32_e32 v30, 0x2000, v30
	s_waitcnt vmcnt(45)
; __device__ __forceinline__ unsigned pack2(float a, float b) { return (unsigned)f2bf(a) | ((unsigned)f2bf(b) << 16); }
; __device__ __forceinline__ float lo16(unsigned v) { return __uint_as_float(v << 16); }
; __device__ __forceinline__ float hi16(unsigned v) { return __uint_as_float(v & 0xffff0000u); }
; __device__ __forceinline__ void phase_scan(const Params& p, unsigned* st, int npairs, int pairs_per_head_shift, int mode) {
;     ...
;   for (int e = blockIdx.x * 256 + tid; e < npairs; e += gridDim.x * 256) {
;     int h = e >> pairs_per_head_shift;
;     float r0 = 0.f, r1 = 0.f;
;     float rdec = 1.f;
;     if (mode == 1) rdec = expf(128.f * logf(1.f - exp2f(-5.f - (float)h)));
;     for (int c0 = 0; c0 < NCH; c0 += 8) {
;       unsigned v[8];
;       float dc[8];
; #pragma unroll
;       for (int i = 0; i < 8; i++) {
;         int c = c0 + i;
;         if (c < NCH) {
;           v[i] = st[(size_t)c * npairs + e];
;           dc[i] = (mode == 0) ? expf(acs[((size_t)c * 16 + h) * 128 + 127]) : rdec;
;         } else { v[i] = 0; dc[i] = 0.f; }
;       }
; #pragma unroll
;       for (int i = 0; i < 8; i++) {
;         int c = c0 + i;
;         if (c < NCH) {
;           *(st + (size_t)c * npairs + e) = pack2(r0, r1);
;           r0 = r0 * dc[i] + lo16(v[i]);
;           r1 = r1 * dc[i] + hi16(v[i]);
;         }
;       }
;     }
;   }
	v_mul_f32_e32 v13, 0x3fb8aa3b, v72
	v_fma_f32 v14, v72, v19, -v13
	v_rndne_f32_e32 v15, v13
	v_fmac_f32_e32 v14, 0x32a5705f, v72
	v_sub_f32_e32 v13, v13, v15
	v_add_f32_e32 v13, v13, v14
	v_exp_f32_e32 v13, v13
	v_cvt_i32_f32_e32 v14, v15
	v_cmp_ngt_f32_e32 vcc, 0xc2ce8ed0, v72
	v_ldexp_f32 v13, v13, v14
	s_nop 0
	v_cndmask_b32_e32 v13, 0, v13, vcc
	v_cmp_nlt_f32_e32 vcc, 0x42b17218, v72
	s_nop 1
	v_cndmask_b32_e32 v12, v16, v13, vcc
	v_bfe_u32 v24, v20, 16, 1
	v_add3_u32 v24, v20, v24, v17
	v_bfe_u32 v25, v21, 16, 1
	v_lshrrev_b32_e32 v24, 16, v24
	v_add3_u32 v25, v21, v25, v17
	v_and_or_b32 v24, v25, v18, v24
	global_store_dword v27, v24, s[6:7]
	v_add_u32_e32 v27, 0x40000, v27
	v_lshlrev_b32_e32 v22, 16, v52
	v_and_b32_e32 v23, 0xffff0000, v52
	v_fmac_f32_e32 v22, v12, v20
	v_fmac_f32_e32 v23, v12, v21
	v_min_u32_e32 v26, v26, v28
	global_load_dword v52, v26, s[6:7]
	v_add_u32_e32 v26, 0x40000, v26
	v_min_u32_e32 v30, v30, v31
	global_load_dword v72, v30, s[8:9]
	v_add_u32_e32 v30, 0x2000, v30
	s_waitcnt vmcnt(45)
	v_mul_f32_e32 v13, 0x3fb8aa3b, v73
	v_fma_f32 v14, v73, v19, -v13
	v_rndne_f32_e32 v15, v13
	v_fmac_f32_e32 v14, 0x32a5705f, v73
	v_sub_f32_e32 v13, v13, v15
	v_add_f32_e32 v13, v13, v14
	v_exp_f32_e32 v13, v13
	v_cvt_i32_f32_e32 v14, v15
	v_cmp_ngt_f32_e32 vcc, 0xc2ce8ed0, v73
	v_ldexp_f32 v13, v13, v14
	s_nop 0
	v_cndmask_b32_e32 v13, 0, v13, vcc
	v_cmp_nlt_f32_e32 vcc, 0x42b17218, v73
	s_nop 1
	v_cndmask_b32_e32 v12, v16, v13, vcc
	v_bfe_u32 v24, v22, 16, 1
	v_add3_u32 v24, v22, v24, v17
	v_bfe_u32 v25, v23, 16, 1
	v_lshrrev_b32_e32 v24, 16, v24
	v_add3_u32 v25, v23, v25, v17
	v_and_or_b32 v24, v25, v18, v24
	global_store_dword v27, v24, s[6:7]
	v_add_u32_e32 v27, 0x40000, v27
	v_lshlrev_b32_e32 v20, 16, v53
	v_and_b32_e32 v21, 0xffff0000, v53
	v_fmac_f32_e32 v20, v12, v22
	v_fmac_f32_e32 v21, v12, v23
	v_min_u32_e32 v26, v26, v28
	global_load_dword v53, v26, s[6:7]
	v_add_u32_e32 v26, 0x40000, v26
	v_min_u32_e32 v30, v30, v31
	global_load_dword v73, v30, s[8:9]
	v_add_u32_e32 v30, 0x2000, v30
	s_waitcnt vmcnt(45)
	v_mul_f32_e32 v13, 0x3fb8aa3b, v74
	v_fma_f32 v14, v74, v19, -v13
	v_rndne_f32_e32 v15, v13
	v_fmac_f32_e32 v14, 0x32a5705f, v74
	v_sub_f32_e32 v13, v13, v15
	v_add_f32_e32 v13, v13, v14
	v_exp_f32_e32 v13, v13
	v_cvt_i32_f32_e32 v14, v15
	v_cmp_ngt_f32_e32 vcc, 0xc2ce8ed0, v74
	v_ldexp_f32 v13, v13, v14
	s_nop 0
	v_cndmask_b32_e32 v13, 0, v13, vcc
	v_cmp_nlt_f32_e32 vcc, 0x42b17218, v74
	s_nop 1
	v_cndmask_b32_e32 v12, v16, v13, vcc
	v_bfe_u32 v24, v20, 16, 1
	v_add3_u32 v24, v20, v24, v17
	v_bfe_u32 v25, v21, 16, 1
	v_lshrrev_b32_e32 v24, 16, v24
	v_add3_u32 v25, v21, v25, v17
	v_and_or_b32 v24, v25, v18, v24
	global_store_dword v27, v24, s[6:7]
	v_add_u32_e32 v27, 0x40000, v27
	v_lshlrev_b32_e32 v22, 16, v54
	v_and_b32_e32 v23, 0xffff0000, v54
	v_fmac_f32_e32 v22, v12, v20
	v_fmac_f32_e32 v23, v12, v21
	v_min_u32_e32 v26, v26, v28
	global_load_dword v54, v26, s[6:7]
	v_add_u32_e32 v26, 0x40000, v26
	v_min_u32_e32 v30, v30, v31
	global_load_dword v74, v30, s[8:9]
	v_add_u32_e32 v30, 0x2000, v30
	s_waitcnt vmcnt(45)
	v_mul_f32_e32 v13, 0x3fb8aa3b, v75
	v_fma_f32 v14, v75, v19, -v13
	v_rndne_f32_e32 v15, v13
	v_fmac_f32_e32 v14, 0x32a5705f, v75
	v_sub_f32_e32 v13, v13, v15
	v_add_f32_e32 v13, v13, v14
	v_exp_f32_e32 v13, v13
	v_cvt_i32_f32_e32 v14, v15
	v_cmp_ngt_f32_e32 vcc, 0xc2ce8ed0, v75
	v_ldexp_f32 v13, v13, v14
	s_nop 0
	v_cndmask_b32_e32 v13, 0, v13, vcc
	v_cmp_nlt_f32_e32 vcc, 0x42b17218, v75
	s_nop 1
	v_cndmask_b32_e32 v12, v16, v13, vcc
	v_bfe_u32 v24, v22, 16, 1
	v_add3_u32 v24, v22, v24, v17
	v_bfe_u32 v25, v23, 16, 1
	v_lshrrev_b32_e32 v24, 16, v24
	v_add3_u32 v25, v23, v25, v17
	v_and_or_b32 v24, v25, v18, v24
	global_store_dword v27, v24, s[6:7]
	v_add_u32_e32 v27, 0x40000, v27
	v_lshlrev_b32_e32 v20, 16, v55
	v_and_b32_e32 v21, 0xffff0000, v55
	v_fmac_f32_e32 v20, v12, v22
	v_fmac_f32_e32 v21, v12, v23
	v_min_u32_e32 v26, v26, v28
	global_load_dword v55, v26, s[6:7]
	v_add_u32_e32 v26, 0x40000, v26
	v_min_u32_e32 v30, v30, v31
	global_load_dword v75, v30, s[8:9]
	v_add_u32_e32 v30, 0x2000, v30
	s_add_i32 m0, m0, -1
	s_cmp_lg_u32 m0, 0
	s_cbranch_scc1 .Lscan_ssd0_loop
	v_bfe_u32 v24, v20, 16, 1
	v_add3_u32 v24, v20, v24, v17
	v_bfe_u32 v25, v21, 16, 1
	v_lshrrev_b32_e32 v24, 16, v24
	v_add3_u32 v25, v21, v25, v17
	v_and_or_b32 v24, v25, v18, v24
	global_store_dword v27, v24, s[6:7]
	s_waitcnt vmcnt(0)
	v_add_u32_e32 v0, s1, v0
	v_cmp_lt_i32_e32 vcc, s90, v0
	s_or_b64 s[10:11], vcc, s[10:11]
	s_andn2_b64 exec, exec, s[10:11]
	s_cbranch_execnz .LBB0_1190

; __device__ __forceinline__ unsigned pack2(float a, float b) { return (unsigned)f2bf(a) | ((unsigned)f2bf(b) << 16); }
; __device__ __forceinline__ float lo16(unsigned v) { return __uint_as_float(v << 16); }
; __device__ __forceinline__ float hi16(unsigned v) { return __uint_as_float(v & 0xffff0000u); }
; __device__ __forceinline__ void phase_scan(const Params& p, unsigned* st, int npairs, int pairs_per_head_shift, int mode) {
;     ...
;   for (int e = blockIdx.x * 256 + tid; e < npairs; e += gridDim.x * 256) {
;     int h = e >> pairs_per_head_shift;
;     float r0 = 0.f, r1 = 0.f;
;     float rdec = 1.f;
;     if (mode == 1) rdec = expf(128.f * logf(1.f - exp2f(-5.f - (float)h)));
;     for (int c0 = 0; c0 < NCH; c0 += 8) {
;       unsigned v[8];
;       float dc[8];
; #pragma unroll
;       for (int i = 0; i < 8; i++) {
;         int c = c0 + i;
;         if (c < NCH) {
;           v[i] = st[(size_t)c * npairs + e];
;           dc[i] = (mode == 0) ? expf(acs[((size_t)c * 16 + h) * 128 + 127]) : rdec;
;         } else { v[i] = 0; dc[i] = 0.f; }
;       }
; #pragma unroll
;       for (int i = 0; i < 8; i++) {
;         int c = c0 + i;
;         if (c < NCH) {
;           *(st + (size_t)c * npairs + e) = pack2(r0, r1);
;           r0 = r0 * dc[i] + lo16(v[i]);
;           r1 = r1 * dc[i] + hi16(v[i]);
;         }
;       }
.LBB0_1446:
	v_ashrrev_i32_e32 v1, 15, v0
	v_cvt_f32_i32_e32 v1, v1
	s_mov_b32 s2, 0xc2fc0000
	v_sub_f32_e32 v1, 0xc0a00000, v1
	v_cmp_gt_f32_e32 vcc, s2, v1
	s_mov_b32 s2, 0x3f317217
	s_nop 0
	v_cndmask_b32_e32 v2, 0, v6, vcc
	v_add_f32_e32 v1, v1, v2
	v_exp_f32_e32 v1, v1
	v_cndmask_b32_e32 v2, 0, v8, vcc
	v_ldexp_f32 v1, v1, v2
	v_sub_f32_e32 v1, 1.0, v1
	v_cmp_gt_f32_e32 vcc, s1, v1
	s_nop 1
	v_cndmask_b32_e64 v2, 0, 32, vcc
	v_ldexp_f32 v1, v1, v2
	v_log_f32_e32 v1, v1
	s_nop 0
	v_mul_f32_e32 v2, 0x3f317217, v1
	v_fma_f32 v2, v1, s2, -v2
	v_fmac_f32_e32 v2, 0x3377d1cf, v1
	s_mov_b32 s2, 0x7f800000
	v_fmac_f32_e32 v2, 0x3f317217, v1
	v_cmp_lt_f32_e64 s[4:5], |v1|, s2
	s_mov_b32 s2, 0x3fb8aa3b
	s_nop 0
	v_cndmask_b32_e64 v1, v1, v2, s[4:5]
	v_cndmask_b32_e32 v2, 0, v9, vcc
	v_sub_f32_e32 v1, v1, v2
	v_mul_f32_e32 v1, 0x43000000, v1
	v_mul_f32_e32 v2, 0x3fb8aa3b, v1
	v_fma_f32 v3, v1, s2, -v2
	v_rndne_f32_e32 v4, v2
	v_fmac_f32_e32 v3, 0x32a5705f, v1
	v_sub_f32_e32 v2, v2, v4
	v_add_f32_e32 v2, v2, v3
	v_exp_f32_e32 v2, v2
	v_cvt_i32_f32_e32 v3, v4
	s_mov_b32 s2, 0xc2ce8ed0
	v_cmp_ngt_f32_e32 vcc, s2, v1
	s_mov_b32 s2, 0x42b17218
	v_ldexp_f32 v2, v2, v3
	v_cndmask_b32_e32 v2, 0, v2, vcc
	v_cmp_nlt_f32_e32 vcc, s2, v1
	v_ashrrev_i32_e32 v1, 31, v0
	s_mov_b32 s2, 0x80000
	v_cndmask_b32_e32 v11, v10, v2, vcc
	v_mov_b32_e32 v17, 0x7fff
	v_mov_b32_e32 v18, 0xffff0000
	v_lshlrev_b32_e32 v26, 2, v0
	v_mov_b32_e32 v20, 0
	v_mov_b32_e32 v21, 0
	v_mov_b32_e32 v27, v26
	v_add_u32_e32 v28, 0x4000000, v26
	global_load_dword v40, v26, s[8:9]
	v_add_u32_e32 v26, 0x80000, v26
	global_load_dword v41, v26, s[8:9]
	v_add_u32_e32 v26, 0x80000, v26
	global_load_dword v42, v26, s[8:9]
	v_add_u32_e32 v26, 0x80000, v26
	global_load_dword v43, v26, s[8:9]
	v_add_u32_e32 v26, 0x80000, v26
	global_load_dword v44, v26, s[8:9]
	v_add_u32_e32 v26, 0x80000, v26
	global_load_dword v45, v26, s[8:9]
	v_add_u32_e32 v26, 0x80000, v26
	global_load_dword v46, v26, s[8:9]
	v_add_u32_e32 v26, 0x80000, v26
	global_load_dword v47, v26, s[8:9]
	v_add_u32_e32 v26, 0x80000, v26
	global_load_dword v48, v26, s[8:9]
	v_add_u32_e32 v26, 0x80000, v26
	global_load_dword v49, v26, s[8:9]
	v_add_u32_e32 v26, 0x80000, v26
	global_load_dword v50, v26, s[8:9]
	v_add_u32_e32 v26, 0x80000, v26
	global_load_dword v51, v26, s[8:9]
	v_add_u32_e32 v26, 0x80000, v26
	global_load_dword v52, v26, s[8:9]
	v_add_u32_e32 v26, 0x80000, v26
	global_load_dword v53, v26, s[8:9]
	v_add_u32_e32 v26, 0x80000, v26
	global_load_dword v54, v26, s[8:9]
	v_add_u32_e32 v26, 0x80000, v26
	global_load_dword v55, v26, s[8:9]
	v_add_u32_e32 v26, 0x80000, v26
	global_load_dword v56, v26, s[8:9]
	v_add_u32_e32 v26, 0x80000, v26
	global_load_dword v57, v26, s[8:9]
	v_add_u32_e32 v26, 0x80000, v26
	global_load_dword v58, v26, s[8:9]
	v_add_u32_e32 v26, 0x80000, v26
	global_load_dword v59, v26, s[8:9]
	v_add_u32_e32 v26, 0x80000, v26
	global_load_dword v60, v26, s[8:9]
	v_add_u32_e32 v26, 0x80000, v26
	global_load_dword v61, v26, s[8:9]
	v_add_u32_e32 v26, 0x80000, v26
	global_load_dword v62, v26, s[8:9]
	v_add_u32_e32 v26, 0x80000, v26
	global_load_dword v63, v26, s[8:9]
	v_add_u32_e32 v26, 0x80000, v26
	global_load_dword v64, v26, s[8:9]
	v_add_u32_e32 v26, 0x80000, v26
	global_load_dword v65, v26, s[8:9]
	v_add_u32_e32 v26, 0x80000, v26
	global_load_dword v66, v26, s[8:9]
	v_add_u32_e32 v26, 0x80000, v26
	global_load_dword v67, v26, s[8:9]
	v_add_u32_e32 v26, 0x80000, v26
	global_load_dword v68, v26, s[8:9]
	v_add_u32_e32 v26, 0x80000, v26
	global_load_dword v69, v26, s[8:9]
	v_add_u32_e32 v26, 0x80000, v26
	global_load_dword v70, v26, s[8:9]
	v_add_u32_e32 v26, 0x80000, v26
	global_load_dword v71, v26, s[8:9]
	v_add_u32_e32 v26, 0x80000, v26
	s_waitcnt vmcnt(31)
	v_bfe_u32 v24, v20, 16, 1
	v_add3_u32 v24, v20, v24, v17
	v_bfe_u32 v25, v21, 16, 1
	v_lshrrev_b32_e32 v24, 16, v24
	v_add3_u32 v25, v21, v25, v17
	v_and_or_b32 v24, v25, v18, v24
	global_store_dword v27, v24, s[8:9]
	v_add_u32_e32 v27, 0x80000, v27
	v_lshlrev_b32_e32 v22, 16, v40
	v_and_b32_e32 v23, 0xffff0000, v40
	v_fmac_f32_e32 v22, v11, v20
	v_fmac_f32_e32 v23, v11, v21
	v_min_u32_e32 v26, v26, v28
	global_load_dword v40, v26, s[8:9]
	v_add_u32_e32 v26, 0x80000, v26
	s_waitcnt vmcnt(32)
	v_bfe_u32 v24, v22, 16, 1
	v_add3_u32 v24, v22, v24, v17
	v_bfe_u32 v25, v23, 16, 1
	v_lshrrev_b32_e32 v24, 16, v24
	v_add3_u32 v25, v23, v25, v17
	v_and_or_b32 v24, v25, v18, v24
	global_store_dword v27, v24, s[8:9]
	v_add_u32_e32 v27, 0x80000, v27
	v_lshlrev_b32_e32 v20, 16, v41
	v_and_b32_e32 v21, 0xffff0000, v41
	v_fmac_f32_e32 v20, v11, v22
	v_fmac_f32_e32 v21, v11, v23
	v_min_u32_e32 v26, v26, v28
	global_load_dword v41, v26, s[8:9]
	v_add_u32_e32 v26, 0x80000, v26
	s_waitcnt vmcnt(33)
	v_bfe_u32 v24, v20, 16, 1
	v_add3_u32 v24, v20, v24, v17
	v_bfe_u32 v25, v21, 16, 1
	v_lshrrev_b32_e32 v24, 16, v24
	v_add3_u32 v25, v21, v25, v17
	v_and_or_b32 v24, v25, v18, v24
	global_store_dword v27, v24, s[8:9]
	v_add_u32_e32 v27, 0x80000, v27
	v_lshlrev_b32_e32 v22, 16, v42
	v_and_b32_e32 v23, 0xffff0000, v42
	v_fmac_f32_e32 v22, v11, v20
	v_fmac_f32_e32 v23, v11, v21
	v_min_u32_e32 v26, v26, v28
	global_load_dword v42, v26, s[8:9]
	v_add_u32_e32 v26, 0x80000, v26
	s_waitcnt vmcnt(34)
	v_bfe_u32 v24, v22, 16, 1
	v_add3_u32 v24, v22, v24, v17
	v_bfe_u32 v25, v23, 16, 1
	v_lshrrev_b32_e32 v24, 16, v24
	v_add3_u32 v25, v23, v25, v17
	v_and_or_b32 v24, v25, v18, v24
	global_store_dword v27, v24, s[8:9]
	v_add_u32_e32 v27, 0x80000, v27
	v_lshlrev_b32_e32 v20, 16, v43
	v_and_b32_e32 v21, 0xffff0000, v43
	v_fmac_f32_e32 v20, v11, v22
	v_fmac_f32_e32 v21, v11, v23
	v_min_u32_e32 v26, v26, v28
	global_load_dword v43, v26, s[8:9]
	v_add_u32_e32 v26, 0x80000, v26
	s_waitcnt vmcnt(35)
; __device__ __forceinline__ unsigned pack2(float a, float b) { return (unsigned)f2bf(a) | ((unsigned)f2bf(b) << 16); }
; __device__ __forceinline__ float lo16(unsigned v) { return __uint_as_float(v << 16); }
; __device__ __forceinline__ float hi16(unsigned v) { return __uint_as_float(v & 0xffff0000u); }
; __device__ __forceinline__ void phase_scan(const Params& p, unsigned* st, int npairs, int pairs_per_head_shift, int mode) {
;     ...
;   for (int e = blockIdx.x * 256 + tid; e < npairs; e += gridDim.x * 256) {
;     int h = e >> pairs_per_head_shift;
;     float r0 = 0.f, r1 = 0.f;
;     float rdec = 1.f;
;     if (mode == 1) rdec = expf(128.f * logf(1.f - exp2f(-5.f - (float)h)));
;     for (int c0 = 0; c0 < NCH; c0 += 8) {
;       unsigned v[8];
;       float dc[8];
; #pragma unroll
;       for (int i = 0; i < 8; i++) {
;         int c = c0 + i;
;         if (c < NCH) {
;           v[i] = st[(size_t)c * npairs + e];
;           dc[i] = (mode == 0) ? expf(acs[((size_t)c * 16 + h) * 128 + 127]) : rdec;
;         } else { v[i] = 0; dc[i] = 0.f; }
;       }
; #pragma unroll
;       for (int i = 0; i < 8; i++) {
;         int c = c0 + i;
;         if (c < NCH) {
;           *(st + (size_t)c * npairs + e) = pack2(r0, r1);
;           r0 = r0 * dc[i] + lo16(v[i]);
;           r1 = r1 * dc[i] + hi16(v[i]);
;         }
;       }
	v_bfe_u32 v24, v20, 16, 1
	v_add3_u32 v24, v20, v24, v17
	v_bfe_u32 v25, v21, 16, 1
	v_lshrrev_b32_e32 v24, 16, v24
	v_add3_u32 v25, v21, v25, v17
	v_and_or_b32 v24, v25, v18, v24
	global_store_dword v27, v24, s[8:9]
	v_add_u32_e32 v27, 0x80000, v27
	v_lshlrev_b32_e32 v22, 16, v44
	v_and_b32_e32 v23, 0xffff0000, v44
	v_fmac_f32_e32 v22, v11, v20
	v_fmac_f32_e32 v23, v11, v21
	v_min_u32_e32 v26, v26, v28
	global_load_dword v44, v26, s[8:9]
	v_add_u32_e32 v26, 0x80000, v26
	s_waitcnt vmcnt(36)
	v_bfe_u32 v24, v22, 16, 1
	v_add3_u32 v24, v22, v24, v17
	v_bfe_u32 v25, v23, 16, 1
	v_lshrrev_b32_e32 v24, 16, v24
	v_add3_u32 v25, v23, v25, v17
	v_and_or_b32 v24, v25, v18, v24
	global_store_dword v27, v24, s[8:9]
	v_add_u32_e32 v27, 0x80000, v27
	v_lshlrev_b32_e32 v20, 16, v45
	v_and_b32_e32 v21, 0xffff0000, v45
	v_fmac_f32_e32 v20, v11, v22
	v_fmac_f32_e32 v21, v11, v23
	v_min_u32_e32 v26, v26, v28
	global_load_dword v45, v26, s[8:9]
	v_add_u32_e32 v26, 0x80000, v26
	s_waitcnt vmcnt(37)
	v_bfe_u32 v24, v20, 16, 1
	v_add3_u32 v24, v20, v24, v17
	v_bfe_u32 v25, v21, 16, 1
	v_lshrrev_b32_e32 v24, 16, v24
	v_add3_u32 v25, v21, v25, v17
	v_and_or_b32 v24, v25, v18, v24
	global_store_dword v27, v24, s[8:9]
	v_add_u32_e32 v27, 0x80000, v27
	v_lshlrev_b32_e32 v22, 16, v46
	v_and_b32_e32 v23, 0xffff0000, v46
	v_fmac_f32_e32 v22, v11, v20
	v_fmac_f32_e32 v23, v11, v21
	v_min_u32_e32 v26, v26, v28
	global_load_dword v46, v26, s[8:9]
	v_add_u32_e32 v26, 0x80000, v26
	s_waitcnt vmcnt(38)
	v_bfe_u32 v24, v22, 16, 1
	v_add3_u32 v24, v22, v24, v17
	v_bfe_u32 v25, v23, 16, 1
	v_lshrrev_b32_e32 v24, 16, v24
	v_add3_u32 v25, v23, v25, v17
	v_and_or_b32 v24, v25, v18, v24
	global_store_dword v27, v24, s[8:9]
	v_add_u32_e32 v27, 0x80000, v27
	v_lshlrev_b32_e32 v20, 16, v47
	v_and_b32_e32 v21, 0xffff0000, v47
	v_fmac_f32_e32 v20, v11, v22
	v_fmac_f32_e32 v21, v11, v23
	v_min_u32_e32 v26, v26, v28
	global_load_dword v47, v26, s[8:9]
	v_add_u32_e32 v26, 0x80000, v26
	s_waitcnt vmcnt(39)
	v_bfe_u32 v24, v20, 16, 1
	v_add3_u32 v24, v20, v24, v17
	v_bfe_u32 v25, v21, 16, 1
	v_lshrrev_b32_e32 v24, 16, v24
	v_add3_u32 v25, v21, v25, v17
	v_and_or_b32 v24, v25, v18, v24
	global_store_dword v27, v24, s[8:9]
	v_add_u32_e32 v27, 0x80000, v27
	v_lshlrev_b32_e32 v22, 16, v48
	v_and_b32_e32 v23, 0xffff0000, v48
	v_fmac_f32_e32 v22, v11, v20
	v_fmac_f32_e32 v23, v11, v21
	v_min_u32_e32 v26, v26, v28
	global_load_dword v48, v26, s[8:9]
	v_add_u32_e32 v26, 0x80000, v26
	s_waitcnt vmcnt(40)
	v_bfe_u32 v24, v22, 16, 1
	v_add3_u32 v24, v22, v24, v17
	v_bfe_u32 v25, v23, 16, 1
	v_lshrrev_b32_e32 v24, 16, v24
	v_add3_u32 v25, v23, v25, v17
	v_and_or_b32 v24, v25, v18, v24
	global_store_dword v27, v24, s[8:9]
	v_add_u32_e32 v27, 0x80000, v27
	v_lshlrev_b32_e32 v20, 16, v49
	v_and_b32_e32 v21, 0xffff0000, v49
	v_fmac_f32_e32 v20, v11, v22
	v_fmac_f32_e32 v21, v11, v23
	v_min_u32_e32 v26, v26, v28
	global_load_dword v49, v26, s[8:9]
	v_add_u32_e32 v26, 0x80000, v26
	s_waitcnt vmcnt(41)
	v_bfe_u32 v24, v20, 16, 1
	v_add3_u32 v24, v20, v24, v17
	v_bfe_u32 v25, v21, 16, 1
	v_lshrrev_b32_e32 v24, 16, v24
	v_add3_u32 v25, v21, v25, v17
	v_and_or_b32 v24, v25, v18, v24
	global_store_dword v27, v24, s[8:9]
	v_add_u32_e32 v27, 0x80000, v27
	v_lshlrev_b32_e32 v22, 16, v50
	v_and_b32_e32 v23, 0xffff0000, v50
	v_fmac_f32_e32 v22, v11, v20
	v_fmac_f32_e32 v23, v11, v21
	v_min_u32_e32 v26, v26, v28
	global_load_dword v50, v26, s[8:9]
	v_add_u32_e32 v26, 0x80000, v26
	s_waitcnt vmcnt(42)
	v_bfe_u32 v24, v22, 16, 1
	v_add3_u32 v24, v22, v24, v17
	v_bfe_u32 v25, v23, 16, 1
	v_lshrrev_b32_e32 v24, 16, v24
	v_add3_u32 v25, v23, v25, v17
	v_and_or_b32 v24, v25, v18, v24
	global_store_dword v27, v24, s[8:9]
	v_add_u32_e32 v27, 0x80000, v27
	v_lshlrev_b32_e32 v20, 16, v51
	v_and_b32_e32 v21, 0xffff0000, v51
	v_fmac_f32_e32 v20, v11, v22
	v_fmac_f32_e32 v21, v11, v23
	v_min_u32_e32 v26, v26, v28
	global_load_dword v51, v26, s[8:9]
	v_add_u32_e32 v26, 0x80000, v26
	s_waitcnt vmcnt(43)
	v_bfe_u32 v24, v20, 16, 1
	v_add3_u32 v24, v20, v24, v17
	v_bfe_u32 v25, v21, 16, 1
	v_lshrrev_b32_e32 v24, 16, v24
	v_add3_u32 v25, v21, v25, v17
	v_and_or_b32 v24, v25, v18, v24
	global_store_dword v27, v24, s[8:9]
	v_add_u32_e32 v27, 0x80000, v27
	v_lshlrev_b32_e32 v22, 16, v52
	v_and_b32_e32 v23, 0xffff0000, v52
	v_fmac_f32_e32 v22, v11, v20
	v_fmac_f32_e32 v23, v11, v21
	v_min_u32_e32 v26, v26, v28
	global_load_dword v52, v26, s[8:9]
	v_add_u32_e32 v26, 0x80000, v26
	s_waitcnt vmcnt(44)
	v_bfe_u32 v24, v22, 16, 1
	v_add3_u32 v24, v22, v24, v17
	v_bfe_u32 v25, v23, 16, 1
	v_lshrrev_b32_e32 v24, 16, v24
	v_add3_u32 v25, v23, v25, v17
	v_and_or_b32 v24, v25, v18, v24
	global_store_dword v27, v24, s[8:9]
	v_add_u32_e32 v27, 0x80000, v27
	v_lshlrev_b32_e32 v20, 16, v53
	v_and_b32_e32 v21, 0xffff0000, v53
	v_fmac_f32_e32 v20, v11, v22
	v_fmac_f32_e32 v21, v11, v23
	v_min_u32_e32 v26, v26, v28
	global_load_dword v53, v26, s[8:9]
	v_add_u32_e32 v26, 0x80000, v26
	s_waitcnt vmcnt(45)
	v_bfe_u32 v24, v20, 16, 1
	v_add3_u32 v24, v20, v24, v17
	v_bfe_u32 v25, v21, 16, 1
	v_lshrrev_b32_e32 v24, 16, v24
	v_add3_u32 v25, v21, v25, v17
	v_and_or_b32 v24, v25, v18, v24
	global_store_dword v27, v24, s[8:9]
	v_add_u32_e32 v27, 0x80000, v27
	v_lshlrev_b32_e32 v22, 16, v54
	v_and_b32_e32 v23, 0xffff0000, v54
	v_fmac_f32_e32 v22, v11, v20
	v_fmac_f32_e32 v23, v11, v21
	v_min_u32_e32 v26, v26, v28
	global_load_dword v54, v26, s[8:9]
	v_add_u32_e32 v26, 0x80000, v26
	s_waitcnt vmcnt(46)
; __device__ __forceinline__ unsigned pack2(float a, float b) { return (unsigned)f2bf(a) | ((unsigned)f2bf(b) << 16); }
; __device__ __forceinline__ float lo16(unsigned v) { return __uint_as_float(v << 16); }
; __device__ __forceinline__ float hi16(unsigned v) { return __uint_as_float(v & 0xffff0000u); }
; __device__ __forceinline__ void phase_scan(const Params& p, unsigned* st, int npairs, int pairs_per_head_shift, int mode) {
;     ...
;   for (int e = blockIdx.x * 256 + tid; e < npairs; e += gridDim.x * 256) {
;     int h = e >> pairs_per_head_shift;
;     float r0 = 0.f, r1 = 0.f;
;     float rdec = 1.f;
;     if (mode == 1) rdec = expf(128.f * logf(1.f - exp2f(-5.f - (float)h)));
;     for (int c0 = 0; c0 < NCH; c0 += 8) {
;       unsigned v[8];
;       float dc[8];
; #pragma unroll
;       for (int i = 0; i < 8; i++) {
;         int c = c0 + i;
;         if (c < NCH) {
;           v[i] = st[(size_t)c * npairs + e];
;           dc[i] = (mode == 0) ? expf(acs[((size_t)c * 16 + h) * 128 + 127]) : rdec;
;         } else { v[i] = 0; dc[i] = 0.f; }
;       }
; #pragma unroll
;       for (int i = 0; i < 8; i++) {
;         int c = c0 + i;
;         if (c < NCH) {
;           *(st + (size_t)c * npairs + e) = pack2(r0, r1);
;           r0 = r0 * dc[i] + lo16(v[i]);
;           r1 = r1 * dc[i] + hi16(v[i]);
;         }
;       }
	v_bfe_u32 v24, v22, 16, 1
	v_add3_u32 v24, v22, v24, v17
	v_bfe_u32 v25, v23, 16, 1
	v_lshrrev_b32_e32 v24, 16, v24
	v_add3_u32 v25, v23, v25, v17
	v_and_or_b32 v24, v25, v18, v24
	global_store_dword v27, v24, s[8:9]
	v_add_u32_e32 v27, 0x80000, v27
	v_lshlrev_b32_e32 v20, 16, v55
	v_and_b32_e32 v21, 0xffff0000, v55
	v_fmac_f32_e32 v20, v11, v22
	v_fmac_f32_e32 v21, v11, v23
	v_min_u32_e32 v26, v26, v28
	global_load_dword v55, v26, s[8:9]
	v_add_u32_e32 v26, 0x80000, v26
	s_waitcnt vmcnt(47)
	v_bfe_u32 v24, v20, 16, 1
	v_add3_u32 v24, v20, v24, v17
	v_bfe_u32 v25, v21, 16, 1
	v_lshrrev_b32_e32 v24, 16, v24
	v_add3_u32 v25, v21, v25, v17
	v_and_or_b32 v24, v25, v18, v24
	global_store_dword v27, v24, s[8:9]
	v_add_u32_e32 v27, 0x80000, v27
	v_lshlrev_b32_e32 v22, 16, v56
	v_and_b32_e32 v23, 0xffff0000, v56
	v_fmac_f32_e32 v22, v11, v20
	v_fmac_f32_e32 v23, v11, v21
	v_min_u32_e32 v26, v26, v28
	global_load_dword v56, v26, s[8:9]
	v_add_u32_e32 v26, 0x80000, v26
	s_waitcnt vmcnt(48)
	v_bfe_u32 v24, v22, 16, 1
	v_add3_u32 v24, v22, v24, v17
	v_bfe_u32 v25, v23, 16, 1
	v_lshrrev_b32_e32 v24, 16, v24
	v_add3_u32 v25, v23, v25, v17
	v_and_or_b32 v24, v25, v18, v24
	global_store_dword v27, v24, s[8:9]
	v_add_u32_e32 v27, 0x80000, v27
	v_lshlrev_b32_e32 v20, 16, v57
	v_and_b32_e32 v21, 0xffff0000, v57
	v_fmac_f32_e32 v20, v11, v22
	v_fmac_f32_e32 v21, v11, v23
	v_min_u32_e32 v26, v26, v28
	global_load_dword v57, v26, s[8:9]
	v_add_u32_e32 v26, 0x80000, v26
	s_waitcnt vmcnt(49)
	v_bfe_u32 v24, v20, 16, 1
	v_add3_u32 v24, v20, v24, v17
	v_bfe_u32 v25, v21, 16, 1
	v_lshrrev_b32_e32 v24, 16, v24
	v_add3_u32 v25, v21, v25, v17
	v_and_or_b32 v24, v25, v18, v24
	global_store_dword v27, v24, s[8:9]
	v_add_u32_e32 v27, 0x80000, v27
	v_lshlrev_b32_e32 v22, 16, v58
	v_and_b32_e32 v23, 0xffff0000, v58
	v_fmac_f32_e32 v22, v11, v20
	v_fmac_f32_e32 v23, v11, v21
	v_min_u32_e32 v26, v26, v28
	global_load_dword v58, v26, s[8:9]
	v_add_u32_e32 v26, 0x80000, v26
	s_waitcnt vmcnt(50)
	v_bfe_u32 v24, v22, 16, 1
	v_add3_u32 v24, v22, v24, v17
	v_bfe_u32 v25, v23, 16, 1
	v_lshrrev_b32_e32 v24, 16, v24
	v_add3_u32 v25, v23, v25, v17
	v_and_or_b32 v24, v25, v18, v24
	global_store_dword v27, v24, s[8:9]
	v_add_u32_e32 v27, 0x80000, v27
	v_lshlrev_b32_e32 v20, 16, v59
	v_and_b32_e32 v21, 0xffff0000, v59
	v_fmac_f32_e32 v20, v11, v22
	v_fmac_f32_e32 v21, v11, v23
	v_min_u32_e32 v26, v26, v28
	global_load_dword v59, v26, s[8:9]
	v_add_u32_e32 v26, 0x80000, v26
	s_waitcnt vmcnt(51)
	v_bfe_u32 v24, v20, 16, 1
	v_add3_u32 v24, v20, v24, v17
	v_bfe_u32 v25, v21, 16, 1
	v_lshrrev_b32_e32 v24, 16, v24
	v_add3_u32 v25, v21, v25, v17
	v_and_or_b32 v24, v25, v18, v24
	global_store_dword v27, v24, s[8:9]
	v_add_u32_e32 v27, 0x80000, v27
	v_lshlrev_b32_e32 v22, 16, v60
	v_and_b32_e32 v23, 0xffff0000, v60
	v_fmac_f32_e32 v22, v11, v20
	v_fmac_f32_e32 v23, v11, v21
	v_min_u32_e32 v26, v26, v28
	global_load_dword v60, v26, s[8:9]
	v_add_u32_e32 v26, 0x80000, v26
	s_waitcnt vmcnt(52)
	v_bfe_u32 v24, v22, 16, 1
	v_add3_u32 v24, v22, v24, v17
	v_bfe_u32 v25, v23, 16, 1
	v_lshrrev_b32_e32 v24, 16, v24
	v_add3_u32 v25, v23, v25, v17
	v_and_or_b32 v24, v25, v18, v24
	global_store_dword v27, v24, s[8:9]
	v_add_u32_e32 v27, 0x80000, v27
	v_lshlrev_b32_e32 v20, 16, v61
	v_and_b32_e32 v21, 0xffff0000, v61
	v_fmac_f32_e32 v20, v11, v22
	v_fmac_f32_e32 v21, v11, v23
	v_min_u32_e32 v26, v26, v28
	global_load_dword v61, v26, s[8:9]
	v_add_u32_e32 v26, 0x80000, v26
	s_waitcnt vmcnt(53)
	v_bfe_u32 v24, v20, 16, 1
	v_add3_u32 v24, v20, v24, v17
	v_bfe_u32 v25, v21, 16, 1
	v_lshrrev_b32_e32 v24, 16, v24
	v_add3_u32 v25, v21, v25, v17
	v_and_or_b32 v24, v25, v18, v24
	global_store_dword v27, v24, s[8:9]
	v_add_u32_e32 v27, 0x80000, v27
	v_lshlrev_b32_e32 v22, 16, v62
	v_and_b32_e32 v23, 0xffff0000, v62
	v_fmac_f32_e32 v22, v11, v20
	v_fmac_f32_e32 v23, v11, v21
	v_min_u32_e32 v26, v26, v28
	global_load_dword v62, v26, s[8:9]
	v_add_u32_e32 v26, 0x80000, v26
	s_waitcnt vmcnt(54)
	v_bfe_u32 v24, v22, 16, 1
	v_add3_u32 v24, v22, v24, v17
	v_bfe_u32 v25, v23, 16, 1
	v_lshrrev_b32_e32 v24, 16, v24
	v_add3_u32 v25, v23, v25, v17
	v_and_or_b32 v24, v25, v18, v24
	global_store_dword v27, v24, s[8:9]
	v_add_u32_e32 v27, 0x80000, v27
	v_lshlrev_b32_e32 v20, 16, v63
	v_and_b32_e32 v21, 0xffff0000, v63
	v_fmac_f32_e32 v20, v11, v22
	v_fmac_f32_e32 v21, v11, v23
	v_min_u32_e32 v26, v26, v28
	global_load_dword v63, v26, s[8:9]
	v_add_u32_e32 v26, 0x80000, v26
	s_waitcnt vmcnt(55)
	v_bfe_u32 v24, v20, 16, 1
	v_add3_u32 v24, v20, v24, v17
	v_bfe_u32 v25, v21, 16, 1
	v_lshrrev_b32_e32 v24, 16, v24
	v_add3_u32 v25, v21, v25, v17
	v_and_or_b32 v24, v25, v18, v24
	global_store_dword v27, v24, s[8:9]
	v_add_u32_e32 v27, 0x80000, v27
	v_lshlrev_b32_e32 v22, 16, v64
	v_and_b32_e32 v23, 0xffff0000, v64
	v_fmac_f32_e32 v22, v11, v20
	v_fmac_f32_e32 v23, v11, v21
	v_min_u32_e32 v26, v26, v28
	global_load_dword v64, v26, s[8:9]
	v_add_u32_e32 v26, 0x80000, v26
	s_waitcnt vmcnt(56)
	v_bfe_u32 v24, v22, 16, 1
	v_add3_u32 v24, v22, v24, v17
	v_bfe_u32 v25, v23, 16, 1
	v_lshrrev_b32_e32 v24, 16, v24
	v_add3_u32 v25, v23, v25, v17
	v_and_or_b32 v24, v25, v18, v24
	global_store_dword v27, v24, s[8:9]
	v_add_u32_e32 v27, 0x80000, v27
	v_lshlrev_b32_e32 v20, 16, v65
	v_and_b32_e32 v21, 0xffff0000, v65
	v_fmac_f32_e32 v20, v11, v22
	v_fmac_f32_e32 v21, v11, v23
	v_min_u32_e32 v26, v26, v28
	global_load_dword v65, v26, s[8:9]
	v_add_u32_e32 v26, 0x80000, v26
	s_waitcnt vmcnt(57)
; __device__ __forceinline__ unsigned pack2(float a, float b) { return (unsigned)f2bf(a) | ((unsigned)f2bf(b) << 16); }
; __device__ __forceinline__ float lo16(unsigned v) { return __uint_as_float(v << 16); }
; __device__ __forceinline__ float hi16(unsigned v) { return __uint_as_float(v & 0xffff0000u); }
; __device__ __forceinline__ void phase_scan(const Params& p, unsigned* st, int npairs, int pairs_per_head_shift, int mode) {
;     ...
;   for (int e = blockIdx.x * 256 + tid; e < npairs; e += gridDim.x * 256) {
;     int h = e >> pairs_per_head_shift;
;     float r0 = 0.f, r1 = 0.f;
;     float rdec = 1.f;
;     if (mode == 1) rdec = expf(128.f * logf(1.f - exp2f(-5.f - (float)h)));
;     for (int c0 = 0; c0 < NCH; c0 += 8) {
;       unsigned v[8];
;       float dc[8];
; #pragma unroll
;       for (int i = 0; i < 8; i++) {
;         int c = c0 + i;
;         if (c < NCH) {
;           v[i] = st[(size_t)c * npairs + e];
;           dc[i] = (mode == 0) ? expf(acs[((size_t)c * 16 + h) * 128 + 127]) : rdec;
;         } else { v[i] = 0; dc[i] = 0.f; }
;       }
; #pragma unroll
;       for (int i = 0; i < 8; i++) {
;         int c = c0 + i;
;         if (c < NCH) {
;           *(st + (size_t)c * npairs + e) = pack2(r0, r1);
;           r0 = r0 * dc[i] + lo16(v[i]);
;           r1 = r1 * dc[i] + hi16(v[i]);
;         }
;       }
	v_bfe_u32 v24, v20, 16, 1
	v_add3_u32 v24, v20, v24, v17
	v_bfe_u32 v25, v21, 16, 1
	v_lshrrev_b32_e32 v24, 16, v24
	v_add3_u32 v25, v21, v25, v17
	v_and_or_b32 v24, v25, v18, v24
	global_store_dword v27, v24, s[8:9]
	v_add_u32_e32 v27, 0x80000, v27
	v_lshlrev_b32_e32 v22, 16, v66
	v_and_b32_e32 v23, 0xffff0000, v66
	v_fmac_f32_e32 v22, v11, v20
	v_fmac_f32_e32 v23, v11, v21
	v_min_u32_e32 v26, v26, v28
	global_load_dword v66, v26, s[8:9]
	v_add_u32_e32 v26, 0x80000, v26
	s_waitcnt vmcnt(58)
	v_bfe_u32 v24, v22, 16, 1
	v_add3_u32 v24, v22, v24, v17
	v_bfe_u32 v25, v23, 16, 1
	v_lshrrev_b32_e32 v24, 16, v24
	v_add3_u32 v25, v23, v25, v17
	v_and_or_b32 v24, v25, v18, v24
	global_store_dword v27, v24, s[8:9]
	v_add_u32_e32 v27, 0x80000, v27
	v_lshlrev_b32_e32 v20, 16, v67
	v_and_b32_e32 v21, 0xffff0000, v67
	v_fmac_f32_e32 v20, v11, v22
	v_fmac_f32_e32 v21, v11, v23
	v_min_u32_e32 v26, v26, v28
	global_load_dword v67, v26, s[8:9]
	v_add_u32_e32 v26, 0x80000, v26
	s_waitcnt vmcnt(59)
	v_bfe_u32 v24, v20, 16, 1
	v_add3_u32 v24, v20, v24, v17
	v_bfe_u32 v25, v21, 16, 1
	v_lshrrev_b32_e32 v24, 16, v24
	v_add3_u32 v25, v21, v25, v17
	v_and_or_b32 v24, v25, v18, v24
	global_store_dword v27, v24, s[8:9]
	v_add_u32_e32 v27, 0x80000, v27
	v_lshlrev_b32_e32 v22, 16, v68
	v_and_b32_e32 v23, 0xffff0000, v68
	v_fmac_f32_e32 v22, v11, v20
	v_fmac_f32_e32 v23, v11, v21
	v_min_u32_e32 v26, v26, v28
	global_load_dword v68, v26, s[8:9]
	v_add_u32_e32 v26, 0x80000, v26
	s_waitcnt vmcnt(60)
	v_bfe_u32 v24, v22, 16, 1
	v_add3_u32 v24, v22, v24, v17
	v_bfe_u32 v25, v23, 16, 1
	v_lshrrev_b32_e32 v24, 16, v24
	v_add3_u32 v25, v23, v25, v17
	v_and_or_b32 v24, v25, v18, v24
	global_store_dword v27, v24, s[8:9]
	v_add_u32_e32 v27, 0x80000, v27
	v_lshlrev_b32_e32 v20, 16, v69
	v_and_b32_e32 v21, 0xffff0000, v69
	v_fmac_f32_e32 v20, v11, v22
	v_fmac_f32_e32 v21, v11, v23
	v_min_u32_e32 v26, v26, v28
	global_load_dword v69, v26, s[8:9]
	v_add_u32_e32 v26, 0x80000, v26
	s_waitcnt vmcnt(61)
	v_bfe_u32 v24, v20, 16, 1
	v_add3_u32 v24, v20, v24, v17
	v_bfe_u32 v25, v21, 16, 1
	v_lshrrev_b32_e32 v24, 16, v24
	v_add3_u32 v25, v21, v25, v17
	v_and_or_b32 v24, v25, v18, v24
	global_store_dword v27, v24, s[8:9]
	v_add_u32_e32 v27, 0x80000, v27
	v_lshlrev_b32_e32 v22, 16, v70
	v_and_b32_e32 v23, 0xffff0000, v70
	v_fmac_f32_e32 v22, v11, v20
	v_fmac_f32_e32 v23, v11, v21
	v_min_u32_e32 v26, v26, v28
	global_load_dword v70, v26, s[8:9]
	v_add_u32_e32 v26, 0x80000, v26
	s_waitcnt vmcnt(62)
	v_bfe_u32 v24, v22, 16, 1
	v_add3_u32 v24, v22, v24, v17
	v_bfe_u32 v25, v23, 16, 1
	v_lshrrev_b32_e32 v24, 16, v24
	v_add3_u32 v25, v23, v25, v17
	v_and_or_b32 v24, v25, v18, v24
	global_store_dword v27, v24, s[8:9]
	v_add_u32_e32 v27, 0x80000, v27
	v_lshlrev_b32_e32 v20, 16, v71
	v_and_b32_e32 v21, 0xffff0000, v71
	v_fmac_f32_e32 v20, v11, v22
	v_fmac_f32_e32 v21, v11, v23
	v_min_u32_e32 v26, v26, v28
	global_load_dword v71, v26, s[8:9]
	v_add_u32_e32 v26, 0x80000, v26
	s_mov_b32 m0, 3
.Lscan_ret0_loop:
	s_waitcnt vmcnt(62)
	v_bfe_u32 v24, v20, 16, 1
	v_add3_u32 v24, v20, v24, v17
	v_bfe_u32 v25, v21, 16, 1
	v_lshrrev_b32_e32 v24, 16, v24
	v_add3_u32 v25, v21, v25, v17
	v_and_or_b32 v24, v25, v18, v24
	global_store_dword v27, v24, s[8:9]
	v_add_u32_e32 v27, 0x80000, v27
	v_lshlrev_b32_e32 v22, 16, v40
	v_and_b32_e32 v23, 0xffff0000, v40
	v_fmac_f32_e32 v22, v11, v20
	v_fmac_f32_e32 v23, v11, v21
	v_min_u32_e32 v26, v26, v28
	global_load_dword v40, v26, s[8:9]
	v_add_u32_e32 v26, 0x80000, v26
	s_waitcnt vmcnt(62)
	v_bfe_u32 v24, v22, 16, 1
	v_add3_u32 v24, v22, v24, v17
	v_bfe_u32 v25, v23, 16, 1
	v_lshrrev_b32_e32 v24, 16, v24
	v_add3_u32 v25, v23, v25, v17
	v_and_or_b32 v24, v25, v18, v24
	global_store_dword v27, v24, s[8:9]
	v_add_u32_e32 v27, 0x80000, v27
	v_lshlrev_b32_e32 v20, 16, v41
	v_and_b32_e32 v21, 0xffff0000, v41
	v_fmac_f32_e32 v20, v11, v22
	v_fmac_f32_e32 v21, v11, v23
	v_min_u32_e32 v26, v26, v28
	global_load_dword v41, v26, s[8:9]
	v_add_u32_e32 v26, 0x80000, v26
	s_waitcnt vmcnt(62)
	v_bfe_u32 v24, v20, 16, 1
	v_add3_u32 v24, v20, v24, v17
	v_bfe_u32 v25, v21, 16, 1
	v_lshrrev_b32_e32 v24, 16, v24
	v_add3_u32 v25, v21, v25, v17
	v_and_or_b32 v24, v25, v18, v24
	global_store_dword v27, v24, s[8:9]
	v_add_u32_e32 v27, 0x80000, v27
	v_lshlrev_b32_e32 v22, 16, v42
	v_and_b32_e32 v23, 0xffff0000, v42
	v_fmac_f32_e32 v22, v11, v20
	v_fmac_f32_e32 v23, v11, v21
	v_min_u32_e32 v26, v26, v28
	global_load_dword v42, v26, s[8:9]
	v_add_u32_e32 v26, 0x80000, v26
	s_waitcnt vmcnt(62)
	v_bfe_u32 v24, v22, 16, 1
	v_add3_u32 v24, v22, v24, v17
	v_bfe_u32 v25, v23, 16, 1
	v_lshrrev_b32_e32 v24, 16, v24
	v_add3_u32 v25, v23, v25, v17
	v_and_or_b32 v24, v25, v18, v24
	global_store_dword v27, v24, s[8:9]
	v_add_u32_e32 v27, 0x80000, v27
	v_lshlrev_b32_e32 v20, 16, v43
	v_and_b32_e32 v21, 0xffff0000, v43
	v_fmac_f32_e32 v20, v11, v22
	v_fmac_f32_e32 v21, v11, v23
	v_min_u32_e32 v26, v26, v28
	global_load_dword v43, v26, s[8:9]
	v_add_u32_e32 v26, 0x80000, v26
	s_waitcnt vmcnt(62)
	v_bfe_u32 v24, v20, 16, 1
	v_add3_u32 v24, v20, v24, v17
	v_bfe_u32 v25, v21, 16, 1
	v_lshrrev_b32_e32 v24, 16, v24
	v_add3_u32 v25, v21, v25, v17
	v_and_or_b32 v24, v25, v18, v24
	global_store_dword v27, v24, s[8:9]
	v_add_u32_e32 v27, 0x80000, v27
	v_lshlrev_b32_e32 v22, 16, v44
	v_and_b32_e32 v23, 0xffff0000, v44
	v_fmac_f32_e32 v22, v11, v20
	v_fmac_f32_e32 v23, v11, v21
	v_min_u32_e32 v26, v26, v28
	global_load_dword v44, v26, s[8:9]
	v_add_u32_e32 v26, 0x80000, v26
	s_waitcnt vmcnt(62)
; __device__ __forceinline__ unsigned pack2(float a, float b) { return (unsigned)f2bf(a) | ((unsigned)f2bf(b) << 16); }
; __device__ __forceinline__ float lo16(unsigned v) { return __uint_as_float(v << 16); }
; __device__ __forceinline__ float hi16(unsigned v) { return __uint_as_float(v & 0xffff0000u); }
; __device__ __forceinline__ void phase_scan(const Params& p, unsigned* st, int npairs, int pairs_per_head_shift, int mode) {
;     ...
;   for (int e = blockIdx.x * 256 + tid; e < npairs; e += gridDim.x * 256) {
;     int h = e >> pairs_per_head_shift;
;     float r0 = 0.f, r1 = 0.f;
;     float rdec = 1.f;
;     if (mode == 1) rdec = expf(128.f * logf(1.f - exp2f(-5.f - (float)h)));
;     for (int c0 = 0; c0 < NCH; c0 += 8) {
;       unsigned v[8];
;       float dc[8];
; #pragma unroll
;       for (int i = 0; i < 8; i++) {
;         int c = c0 + i;
;         if (c < NCH) {
;           v[i] = st[(size_t)c * npairs + e];
;           dc[i] = (mode == 0) ? expf(acs[((size_t)c * 16 + h) * 128 + 127]) : rdec;
;         } else { v[i] = 0; dc[i] = 0.f; }
;       }
; #pragma unroll
;       for (int i = 0; i < 8; i++) {
;         int c = c0 + i;
;         if (c < NCH) {
;           *(st + (size_t)c * npairs + e) = pack2(r0, r1);
;           r0 = r0 * dc[i] + lo16(v[i]);
;           r1 = r1 * dc[i] + hi16(v[i]);
;         }
;       }
	v_bfe_u32 v24, v22, 16, 1
	v_add3_u32 v24, v22, v24, v17
	v_bfe_u32 v25, v23, 16, 1
	v_lshrrev_b32_e32 v24, 16, v24
	v_add3_u32 v25, v23, v25, v17
	v_and_or_b32 v24, v25, v18, v24
	global_store_dword v27, v24, s[8:9]
	v_add_u32_e32 v27, 0x80000, v27
	v_lshlrev_b32_e32 v20, 16, v45
	v_and_b32_e32 v21, 0xffff0000, v45
	v_fmac_f32_e32 v20, v11, v22
	v_fmac_f32_e32 v21, v11, v23
	v_min_u32_e32 v26, v26, v28
	global_load_dword v45, v26, s[8:9]
	v_add_u32_e32 v26, 0x80000, v26
	s_waitcnt vmcnt(62)
	v_bfe_u32 v24, v20, 16, 1
	v_add3_u32 v24, v20, v24, v17
	v_bfe_u32 v25, v21, 16, 1
	v_lshrrev_b32_e32 v24, 16, v24
	v_add3_u32 v25, v21, v25, v17
	v_and_or_b32 v24, v25, v18, v24
	global_store_dword v27, v24, s[8:9]
	v_add_u32_e32 v27, 0x80000, v27
	v_lshlrev_b32_e32 v22, 16, v46
	v_and_b32_e32 v23, 0xffff0000, v46
	v_fmac_f32_e32 v22, v11, v20
	v_fmac_f32_e32 v23, v11, v21
	v_min_u32_e32 v26, v26, v28
	global_load_dword v46, v26, s[8:9]
	v_add_u32_e32 v26, 0x80000, v26
	s_waitcnt vmcnt(62)
	v_bfe_u32 v24, v22, 16, 1
	v_add3_u32 v24, v22, v24, v17
	v_bfe_u32 v25, v23, 16, 1
	v_lshrrev_b32_e32 v24, 16, v24
	v_add3_u32 v25, v23, v25, v17
	v_and_or_b32 v24, v25, v18, v24
	global_store_dword v27, v24, s[8:9]
	v_add_u32_e32 v27, 0x80000, v27
	v_lshlrev_b32_e32 v20, 16, v47
	v_and_b32_e32 v21, 0xffff0000, v47
	v_fmac_f32_e32 v20, v11, v22
	v_fmac_f32_e32 v21, v11, v23
	v_min_u32_e32 v26, v26, v28
	global_load_dword v47, v26, s[8:9]
	v_add_u32_e32 v26, 0x80000, v26
	s_waitcnt vmcnt(62)
	v_bfe_u32 v24, v20, 16, 1
	v_add3_u32 v24, v20, v24, v17
	v_bfe_u32 v25, v21, 16, 1
	v_lshrrev_b32_e32 v24, 16, v24
	v_add3_u32 v25, v21, v25, v17
	v_and_or_b32 v24, v25, v18, v24
	global_store_dword v27, v24, s[8:9]
	v_add_u32_e32 v27, 0x80000, v27
	v_lshlrev_b32_e32 v22, 16, v48
	v_and_b32_e32 v23, 0xffff0000, v48
	v_fmac_f32_e32 v22, v11, v20
	v_fmac_f32_e32 v23, v11, v21
	v_min_u32_e32 v26, v26, v28
	global_load_dword v48, v26, s[8:9]
	v_add_u32_e32 v26, 0x80000, v26
	s_waitcnt vmcnt(62)
	v_bfe_u32 v24, v22, 16, 1
	v_add3_u32 v24, v22, v24, v17
	v_bfe_u32 v25, v23, 16, 1
	v_lshrrev_b32_e32 v24, 16, v24
	v_add3_u32 v25, v23, v25, v17
	v_and_or_b32 v24, v25, v18, v24
	global_store_dword v27, v24, s[8:9]
	v_add_u32_e32 v27, 0x80000, v27
	v_lshlrev_b32_e32 v20, 16, v49
	v_and_b32_e32 v21, 0xffff0000, v49
	v_fmac_f32_e32 v20, v11, v22
	v_fmac_f32_e32 v21, v11, v23
	v_min_u32_e32 v26, v26, v28
	global_load_dword v49, v26, s[8:9]
	v_add_u32_e32 v26, 0x80000, v26
	s_waitcnt vmcnt(62)
	v_bfe_u32 v24, v20, 16, 1
	v_add3_u32 v24, v20, v24, v17
	v_bfe_u32 v25, v21, 16, 1
	v_lshrrev_b32_e32 v24, 16, v24
	v_add3_u32 v25, v21, v25, v17
	v_and_or_b32 v24, v25, v18, v24
	global_store_dword v27, v24, s[8:9]
	v_add_u32_e32 v27, 0x80000, v27
	v_lshlrev_b32_e32 v22, 16, v50
	v_and_b32_e32 v23, 0xffff0000, v50
	v_fmac_f32_e32 v22, v11, v20
	v_fmac_f32_e32 v23, v11, v21
	v_min_u32_e32 v26, v26, v28
	global_load_dword v50, v26, s[8:9]
	v_add_u32_e32 v26, 0x80000, v26
	s_waitcnt vmcnt(62)
	v_bfe_u32 v24, v22, 16, 1
	v_add3_u32 v24, v22, v24, v17
	v_bfe_u32 v25, v23, 16, 1
	v_lshrrev_b32_e32 v24, 16, v24
	v_add3_u32 v25, v23, v25, v17
	v_and_or_b32 v24, v25, v18, v24
	global_store_dword v27, v24, s[8:9]
	v_add_u32_e32 v27, 0x80000, v27
	v_lshlrev_b32_e32 v20, 16, v51
	v_and_b32_e32 v21, 0xffff0000, v51
	v_fmac_f32_e32 v20, v11, v22
	v_fmac_f32_e32 v21, v11, v23
	v_min_u32_e32 v26, v26, v28
	global_load_dword v51, v26, s[8:9]
	v_add_u32_e32 v26, 0x80000, v26
	s_waitcnt vmcnt(62)
	v_bfe_u32 v24, v20, 16, 1
	v_add3_u32 v24, v20, v24, v17
	v_bfe_u32 v25, v21, 16, 1
	v_lshrrev_b32_e32 v24, 16, v24
	v_add3_u32 v25, v21, v25, v17
	v_and_or_b32 v24, v25, v18, v24
	global_store_dword v27, v24, s[8:9]
	v_add_u32_e32 v27, 0x80000, v27
	v_lshlrev_b32_e32 v22, 16, v52
	v_and_b32_e32 v23, 0xffff0000, v52
	v_fmac_f32_e32 v22, v11, v20
	v_fmac_f32_e32 v23, v11, v21
	v_min_u32_e32 v26, v26, v28
	global_load_dword v52, v26, s[8:9]
	v_add_u32_e32 v26, 0x80000, v26
	s_waitcnt vmcnt(62)
	v_bfe_u32 v24, v22, 16, 1
	v_add3_u32 v24, v22, v24, v17
	v_bfe_u32 v25, v23, 16, 1
	v_lshrrev_b32_e32 v24, 16, v24
	v_add3_u32 v25, v23, v25, v17
	v_and_or_b32 v24, v25, v18, v24
	global_store_dword v27, v24, s[8:9]
	v_add_u32_e32 v27, 0x80000, v27
	v_lshlrev_b32_e32 v20, 16, v53
	v_and_b32_e32 v21, 0xffff0000, v53
	v_fmac_f32_e32 v20, v11, v22
	v_fmac_f32_e32 v21, v11, v23
	v_min_u32_e32 v26, v26, v28
	global_load_dword v53, v26, s[8:9]
	v_add_u32_e32 v26, 0x80000, v26
	s_waitcnt vmcnt(62)
	v_bfe_u32 v24, v20, 16, 1
	v_add3_u32 v24, v20, v24, v17
	v_bfe_u32 v25, v21, 16, 1
	v_lshrrev_b32_e32 v24, 16, v24
	v_add3_u32 v25, v21, v25, v17
	v_and_or_b32 v24, v25, v18, v24
	global_store_dword v27, v24, s[8:9]
	v_add_u32_e32 v27, 0x80000, v27
	v_lshlrev_b32_e32 v22, 16, v54
	v_and_b32_e32 v23, 0xffff0000, v54
	v_fmac_f32_e32 v22, v11, v20
	v_fmac_f32_e32 v23, v11, v21
	v_min_u32_e32 v26, v26, v28
	global_load_dword v54, v26, s[8:9]
	v_add_u32_e32 v26, 0x80000, v26
	s_waitcnt vmcnt(62)
	v_bfe_u32 v24, v22, 16, 1
	v_add3_u32 v24, v22, v24, v17
	v_bfe_u32 v25, v23, 16, 1
	v_lshrrev_b32_e32 v24, 16, v24
	v_add3_u32 v25, v23, v25, v17
	v_and_or_b32 v24, v25, v18, v24
	global_store_dword v27, v24, s[8:9]
	v_add_u32_e32 v27, 0x80000, v27
	v_lshlrev_b32_e32 v20, 16, v55
	v_and_b32_e32 v21, 0xffff0000, v55
	v_fmac_f32_e32 v20, v11, v22
	v_fmac_f32_e32 v21, v11, v23
	v_min_u32_e32 v26, v26, v28
	global_load_dword v55, v26, s[8:9]
	v_add_u32_e32 v26, 0x80000, v26
	s_waitcnt vmcnt(62)
; __device__ __forceinline__ unsigned pack2(float a, float b) { return (unsigned)f2bf(a) | ((unsigned)f2bf(b) << 16); }
; __device__ __forceinline__ float lo16(unsigned v) { return __uint_as_float(v << 16); }
; __device__ __forceinline__ float hi16(unsigned v) { return __uint_as_float(v & 0xffff0000u); }
; __device__ __forceinline__ void phase_scan(const Params& p, unsigned* st, int npairs, int pairs_per_head_shift, int mode) {
;     ...
;   for (int e = blockIdx.x * 256 + tid; e < npairs; e += gridDim.x * 256) {
;     int h = e >> pairs_per_head_shift;
;     float r0 = 0.f, r1 = 0.f;
;     float rdec = 1.f;
;     if (mode == 1) rdec = expf(128.f * logf(1.f - exp2f(-5.f - (float)h)));
;     for (int c0 = 0; c0 < NCH; c0 += 8) {
;       unsigned v[8];
;       float dc[8];
; #pragma unroll
;       for (int i = 0; i < 8; i++) {
;         int c = c0 + i;
;         if (c < NCH) {
;           v[i] = st[(size_t)c * npairs + e];
;           dc[i] = (mode == 0) ? expf(acs[((size_t)c * 16 + h) * 128 + 127]) : rdec;
;         } else { v[i] = 0; dc[i] = 0.f; }
;       }
; #pragma unroll
;       for (int i = 0; i < 8; i++) {
;         int c = c0 + i;
;         if (c < NCH) {
;           *(st + (size_t)c * npairs + e) = pack2(r0, r1);
;           r0 = r0 * dc[i] + lo16(v[i]);
;           r1 = r1 * dc[i] + hi16(v[i]);
;         }
;       }
	v_bfe_u32 v24, v20, 16, 1
	v_add3_u32 v24, v20, v24, v17
	v_bfe_u32 v25, v21, 16, 1
	v_lshrrev_b32_e32 v24, 16, v24
	v_add3_u32 v25, v21, v25, v17
	v_and_or_b32 v24, v25, v18, v24
	global_store_dword v27, v24, s[8:9]
	v_add_u32_e32 v27, 0x80000, v27
	v_lshlrev_b32_e32 v22, 16, v56
	v_and_b32_e32 v23, 0xffff0000, v56
	v_fmac_f32_e32 v22, v11, v20
	v_fmac_f32_e32 v23, v11, v21
	v_min_u32_e32 v26, v26, v28
	global_load_dword v56, v26, s[8:9]
	v_add_u32_e32 v26, 0x80000, v26
	s_waitcnt vmcnt(62)
	v_bfe_u32 v24, v22, 16, 1
	v_add3_u32 v24, v22, v24, v17
	v_bfe_u32 v25, v23, 16, 1
	v_lshrrev_b32_e32 v24, 16, v24
	v_add3_u32 v25, v23, v25, v17
	v_and_or_b32 v24, v25, v18, v24
	global_store_dword v27, v24, s[8:9]
	v_add_u32_e32 v27, 0x80000, v27
	v_lshlrev_b32_e32 v20, 16, v57
	v_and_b32_e32 v21, 0xffff0000, v57
	v_fmac_f32_e32 v20, v11, v22
	v_fmac_f32_e32 v21, v11, v23
	v_min_u32_e32 v26, v26, v28
	global_load_dword v57, v26, s[8:9]
	v_add_u32_e32 v26, 0x80000, v26
	s_waitcnt vmcnt(62)
	v_bfe_u32 v24, v20, 16, 1
	v_add3_u32 v24, v20, v24, v17
	v_bfe_u32 v25, v21, 16, 1
	v_lshrrev_b32_e32 v24, 16, v24
	v_add3_u32 v25, v21, v25, v17
	v_and_or_b32 v24, v25, v18, v24
	global_store_dword v27, v24, s[8:9]
	v_add_u32_e32 v27, 0x80000, v27
	v_lshlrev_b32_e32 v22, 16, v58
	v_and_b32_e32 v23, 0xffff0000, v58
	v_fmac_f32_e32 v22, v11, v20
	v_fmac_f32_e32 v23, v11, v21
	v_min_u32_e32 v26, v26, v28
	global_load_dword v58, v26, s[8:9]
	v_add_u32_e32 v26, 0x80000, v26
	s_waitcnt vmcnt(62)
	v_bfe_u32 v24, v22, 16, 1
	v_add3_u32 v24, v22, v24, v17
	v_bfe_u32 v25, v23, 16, 1
	v_lshrrev_b32_e32 v24, 16, v24
	v_add3_u32 v25, v23, v25, v17
	v_and_or_b32 v24, v25, v18, v24
	global_store_dword v27, v24, s[8:9]
	v_add_u32_e32 v27, 0x80000, v27
	v_lshlrev_b32_e32 v20, 16, v59
	v_and_b32_e32 v21, 0xffff0000, v59
	v_fmac_f32_e32 v20, v11, v22
	v_fmac_f32_e32 v21, v11, v23
	v_min_u32_e32 v26, v26, v28
	global_load_dword v59, v26, s[8:9]
	v_add_u32_e32 v26, 0x80000, v26
	s_waitcnt vmcnt(62)
	v_bfe_u32 v24, v20, 16, 1
	v_add3_u32 v24, v20, v24, v17
	v_bfe_u32 v25, v21, 16, 1
	v_lshrrev_b32_e32 v24, 16, v24
	v_add3_u32 v25, v21, v25, v17
	v_and_or_b32 v24, v25, v18, v24
	global_store_dword v27, v24, s[8:9]
	v_add_u32_e32 v27, 0x80000, v27
	v_lshlrev_b32_e32 v22, 16, v60
	v_and_b32_e32 v23, 0xffff0000, v60
	v_fmac_f32_e32 v22, v11, v20
	v_fmac_f32_e32 v23, v11, v21
	v_min_u32_e32 v26, v26, v28
	global_load_dword v60, v26, s[8:9]
	v_add_u32_e32 v26, 0x80000, v26
	s_waitcnt vmcnt(62)
	v_bfe_u32 v24, v22, 16, 1
	v_add3_u32 v24, v22, v24, v17
	v_bfe_u32 v25, v23, 16, 1
	v_lshrrev_b32_e32 v24, 16, v24
	v_add3_u32 v25, v23, v25, v17
	v_and_or_b32 v24, v25, v18, v24
	global_store_dword v27, v24, s[8:9]
	v_add_u32_e32 v27, 0x80000, v27
	v_lshlrev_b32_e32 v20, 16, v61
	v_and_b32_e32 v21, 0xffff0000, v61
	v_fmac_f32_e32 v20, v11, v22
	v_fmac_f32_e32 v21, v11, v23
	v_min_u32_e32 v26, v26, v28
	global_load_dword v61, v26, s[8:9]
	v_add_u32_e32 v26, 0x80000, v26
	s_waitcnt vmcnt(62)
	v_bfe_u32 v24, v20, 16, 1
	v_add3_u32 v24, v20, v24, v17
	v_bfe_u32 v25, v21, 16, 1
	v_lshrrev_b32_e32 v24, 16, v24
	v_add3_u32 v25, v21, v25, v17
	v_and_or_b32 v24, v25, v18, v24
	global_store_dword v27, v24, s[8:9]
	v_add_u32_e32 v27, 0x80000, v27
	v_lshlrev_b32_e32 v22, 16, v62
	v_and_b32_e32 v23, 0xffff0000, v62
	v_fmac_f32_e32 v22, v11, v20
	v_fmac_f32_e32 v23, v11, v21
	v_min_u32_e32 v26, v26, v28
	global_load_dword v62, v26, s[8:9]
	v_add_u32_e32 v26, 0x80000, v26
	s_waitcnt vmcnt(62)
	v_bfe_u32 v24, v22, 16, 1
	v_add3_u32 v24, v22, v24, v17
	v_bfe_u32 v25, v23, 16, 1
	v_lshrrev_b32_e32 v24, 16, v24
	v_add3_u32 v25, v23, v25, v17
	v_and_or_b32 v24, v25, v18, v24
	global_store_dword v27, v24, s[8:9]
	v_add_u32_e32 v27, 0x80000, v27
	v_lshlrev_b32_e32 v20, 16, v63
	v_and_b32_e32 v21, 0xffff0000, v63
	v_fmac_f32_e32 v20, v11, v22
	v_fmac_f32_e32 v21, v11, v23
	v_min_u32_e32 v26, v26, v28
	global_load_dword v63, v26, s[8:9]
	v_add_u32_e32 v26, 0x80000, v26
	s_waitcnt vmcnt(62)
; __device__ __forceinline__ unsigned pack2(float a, float b) { return (unsigned)f2bf(a) | ((unsigned)f2bf(b) << 16); }
; __device__ __forceinline__ float lo16(unsigned v) { return __uint_as_float(v << 16); }
; __device__ __forceinline__ float hi16(unsigned v) { return __uint_as_float(v & 0xffff0000u); }
; __device__ __forceinline__ void phase_scan(const Params& p, unsigned* st, int npairs, int pairs_per_head_shift, int mode) {
;     ...
;   for (int e = blockIdx.x * 256 + tid; e < npairs; e += gridDim.x * 256) {
;     int h = e >> pairs_per_head_shift;
;     float r0 = 0.f, r1 = 0.f;
;     float rdec = 1.f;
;     if (mode == 1) rdec = expf(128.f * logf(1.f - exp2f(-5.f - (float)h)));
;     for (int c0 = 0; c0 < NCH; c0 += 8) {
;       unsigned v[8];
;       float dc[8];
; #pragma unroll
;       for (int i = 0; i < 8; i++) {
;         int c = c0 + i;
;         if (c < NCH) {
;           v[i] = st[(size_t)c * npairs + e];
;           dc[i] = (mode == 0) ? expf(acs[((size_t)c * 16 + h) * 128 + 127]) : rdec;
;         } else { v[i] = 0; dc[i] = 0.f; }
;       }
; #pragma unroll
;       for (int i = 0; i < 8; i++) {
;         int c = c0 + i;
;         if (c < NCH) {
;           *(st + (size_t)c * npairs + e) = pack2(r0, r1);
;           r0 = r0 * dc[i] + lo16(v[i]);
;           r1 = r1 * dc[i] + hi16(v[i]);
;         }
;       }
	v_bfe_u32 v24, v20, 16, 1
	v_add3_u32 v24, v20, v24, v17
	v_bfe_u32 v25, v21, 16, 1
	v_lshrrev_b32_e32 v24, 16, v24
	v_add3_u32 v25, v21, v25, v17
	v_and_or_b32 v24, v25, v18, v24
	global_store_dword v27, v24, s[8:9]
	v_add_u32_e32 v27, 0x80000, v27
	v_lshlrev_b32_e32 v22, 16, v64
	v_and_b32_e32 v23, 0xffff0000, v64
	v_fmac_f32_e32 v22, v11, v20
	v_fmac_f32_e32 v23, v11, v21
	v_min_u32_e32 v26, v26, v28
	global_load_dword v64, v26, s[8:9]
	v_add_u32_e32 v26, 0x80000, v26
	s_waitcnt vmcnt(62)
	v_bfe_u32 v24, v22, 16, 1
	v_add3_u32 v24, v22, v24, v17
	v_bfe_u32 v25, v23, 16, 1
	v_lshrrev_b32_e32 v24, 16, v24
	v_add3_u32 v25, v23, v25, v17
	v_and_or_b32 v24, v25, v18, v24
	global_store_dword v27, v24, s[8:9]
	v_add_u32_e32 v27, 0x80000, v27
	v_lshlrev_b32_e32 v20, 16, v65
	v_and_b32_e32 v21, 0xffff0000, v65
	v_fmac_f32_e32 v20, v11, v22
	v_fmac_f32_e32 v21, v11, v23
	v_min_u32_e32 v26, v26, v28
	global_load_dword v65, v26, s[8:9]
	v_add_u32_e32 v26, 0x80000, v26
	s_waitcnt vmcnt(62)
	v_bfe_u32 v24, v20, 16, 1
	v_add3_u32 v24, v20, v24, v17
	v_bfe_u32 v25, v21, 16, 1
	v_lshrrev_b32_e32 v24, 16, v24
	v_add3_u32 v25, v21, v25, v17
	v_and_or_b32 v24, v25, v18, v24
	global_store_dword v27, v24, s[8:9]
	v_add_u32_e32 v27, 0x80000, v27
	v_lshlrev_b32_e32 v22, 16, v66
	v_and_b32_e32 v23, 0xffff0000, v66
	v_fmac_f32_e32 v22, v11, v20
	v_fmac_f32_e32 v23, v11, v21
	v_min_u32_e32 v26, v26, v28
	global_load_dword v66, v26, s[8:9]
	v_add_u32_e32 v26, 0x80000, v26
	s_waitcnt vmcnt(62)
	v_bfe_u32 v24, v22, 16, 1
	v_add3_u32 v24, v22, v24, v17
	v_bfe_u32 v25, v23, 16, 1
	v_lshrrev_b32_e32 v24, 16, v24
	v_add3_u32 v25, v23, v25, v17
	v_and_or_b32 v24, v25, v18, v24
	global_store_dword v27, v24, s[8:9]
	v_add_u32_e32 v27, 0x80000, v27
	v_lshlrev_b32_e32 v20, 16, v67
	v_and_b32_e32 v21, 0xffff0000, v67
	v_fmac_f32_e32 v20, v11, v22
	v_fmac_f32_e32 v21, v11, v23
	v_min_u32_e32 v26, v26, v28
	global_load_dword v67, v26, s[8:9]
	v_add_u32_e32 v26, 0x80000, v26
	s_waitcnt vmcnt(62)
	v_bfe_u32 v24, v20, 16, 1
	v_add3_u32 v24, v20, v24, v17
	v_bfe_u32 v25, v21, 16, 1
	v_lshrrev_b32_e32 v24, 16, v24
	v_add3_u32 v25, v21, v25, v17
	v_and_or_b32 v24, v25, v18, v24
	global_store_dword v27, v24, s[8:9]
	v_add_u32_e32 v27, 0x80000, v27
	v_lshlrev_b32_e32 v22, 16, v68
	v_and_b32_e32 v23, 0xffff0000, v68
	v_fmac_f32_e32 v22, v11, v20
	v_fmac_f32_e32 v23, v11, v21
	v_min_u32_e32 v26, v26, v28
	global_load_dword v68, v26, s[8:9]
	v_add_u32_e32 v26, 0x80000, v26
	s_waitcnt vmcnt(62)
	v_bfe_u32 v24, v22, 16, 1
	v_add3_u32 v24, v22, v24, v17
	v_bfe_u32 v25, v23, 16, 1
	v_lshrrev_b32_e32 v24, 16, v24
	v_add3_u32 v25, v23, v25, v17
	v_and_or_b32 v24, v25, v18, v24
	global_store_dword v27, v24, s[8:9]
	v_add_u32_e32 v27, 0x80000, v27
	v_lshlrev_b32_e32 v20, 16, v69
	v_and_b32_e32 v21, 0xffff0000, v69
	v_fmac_f32_e32 v20, v11, v22
	v_fmac_f32_e32 v21, v11, v23
	v_min_u32_e32 v26, v26, v28
	global_load_dword v69, v26, s[8:9]
	v_add_u32_e32 v26, 0x80000, v26
	s_waitcnt vmcnt(62)
	v_bfe_u32 v24, v20, 16, 1
	v_add3_u32 v24, v20, v24, v17
	v_bfe_u32 v25, v21, 16, 1
	v_lshrrev_b32_e32 v24, 16, v24
	v_add3_u32 v25, v21, v25, v17
	v_and_or_b32 v24, v25, v18, v24
	global_store_dword v27, v24, s[8:9]
	v_add_u32_e32 v27, 0x80000, v27
	v_lshlrev_b32_e32 v22, 16, v70
	v_and_b32_e32 v23, 0xffff0000, v70
	v_fmac_f32_e32 v22, v11, v20
	v_fmac_f32_e32 v23, v11, v21
	v_min_u32_e32 v26, v26, v28
	global_load_dword v70, v26, s[8:9]
	v_add_u32_e32 v26, 0x80000, v26
	s_waitcnt vmcnt(62)
	v_bfe_u32 v24, v22, 16, 1
	v_add3_u32 v24, v22, v24, v17
	v_bfe_u32 v25, v23, 16, 1
	v_lshrrev_b32_e32 v24, 16, v24
	v_add3_u32 v25, v23, v25, v17
	v_and_or_b32 v24, v25, v18, v24
	global_store_dword v27, v24, s[8:9]
	v_add_u32_e32 v27, 0x80000, v27
	v_lshlrev_b32_e32 v20, 16, v71
	v_and_b32_e32 v21, 0xffff0000, v71
	v_fmac_f32_e32 v20, v11, v22
	v_fmac_f32_e32 v21, v11, v23
	v_min_u32_e32 v26, v26, v28
	global_load_dword v71, v26, s[8:9]
	v_add_u32_e32 v26, 0x80000, v26
	s_add_i32 m0, m0, -1
	s_cmp_lg_u32 m0, 0
	s_cbranch_scc1 .Lscan_ret0_loop
	v_bfe_u32 v24, v20, 16, 1
	v_add3_u32 v24, v20, v24, v17
	v_bfe_u32 v25, v21, 16, 1
	v_lshrrev_b32_e32 v24, 16, v24
	v_add3_u32 v25, v21, v25, v17
	v_and_or_b32 v24, v25, v18, v24
	global_store_dword v27, v24, s[8:9]
	s_waitcnt vmcnt(0)
	v_add_u32_e32 v0, s0, v0
	v_cmp_lt_i32_e32 vcc, s92, v0
	s_or_b64 s[10:11], vcc, s[10:11]
	s_andn2_b64 exec, exec, s[10:11]
	s_cbranch_execnz .LBB0_1446
